# meta-row skinny GEMMs: operand loads of all K steps issued up front into separate registers instead of one load, full wait, one MFMA at a time
# speedup vs baseline: 1.0100x; 1.0100x over previous
; template <class Epi, class Pre>
; __device__ __forceinline__ void meta_gemm(const bf16_t* __restrict__ A, int lda, const bf16_t* __restrict__ Bt, int ldb, int N, int K, Epi& epi, Pre pre) {
;     ...
;     const bf16_t* ap = A + (size_t)(NREAL + fr) * lda + wid * ks + fq * 8;
;     const bf16_t* bp = Bt + (size_t)(cb + fr) * ldb + wid * ks + fq * 8;
; #pragma unroll 4
;     for (int k0 = 0; k0 < ks; k0 += 32) {
;       const bf16x8 a = *(const bf16x8*)(ap + k0);
; #pragma unroll
;       for (int bj = 0; bj < 2; ++bj)
; #pragma unroll
;         for (int n = 0; n < 2; ++n) { const bf16x8 b = *(const bf16x8*)(bp + (size_t)(bj * 128 + n * 16) * ldb + k0); acc[bj][n] = __builtin_amdgcn_mfma_f32_16x16x32_bf16(b, a, acc[bj][n], 0, 0, 0); }
;     }
; #pragma unroll
;     for (int bj = 0; bj < 2; ++bj)
; #pragma unroll
;       for (int n = 0; n < 2; ++n)
; #pragma unroll
;         for (int j = 0; j < 4; ++j) part[(wid * 16 + (bj * 2 + n) * 4 + j) * 64 + lane] = acc[bj][n][j];
;     __syncthreads();
.LBB0_239:
	s_and_b32 s6, s1, 0x60
	s_and_b32 s7, s0, 0xffffff00
	s_or_b32 s6, s7, s6
	v_or_b32_e32 v18, s6, v118
	v_ashrrev_i32_e32 v19, 31, v18
	v_lshlrev_b64 v[18:19], 11, v[18:19]
	v_lshl_add_u64 v[66:67], v[24:25], 0, v[18:19]
	v_add_co_u32_e32 v68, vcc, 0x8000, v66
	global_load_dwordx4 v[18:21], v[66:67], off
	global_load_dwordx4 v[58:61], v[66:67], off offset:64
	v_addc_co_u32_e32 v69, vcc, 0, v67, vcc
	global_load_dwordx4 v[50:53], v[68:69], off
	global_load_dwordx4 v[62:65], v[68:69], off offset:64
	v_add_co_u32_e32 v70, vcc, 0x40000, v66
	v_addc_co_u32_e32 v71, vcc, 0, v67, vcc
	v_add_co_u32_e32 v72, vcc, 0x48000, v66
	v_addc_co_u32_e32 v73, vcc, 0, v67, vcc
	global_load_dwordx4 v[160:163], v[70:71], off
	global_load_dwordx4 v[168:171], v[70:71], off offset:64
	global_load_dwordx4 v[172:175], v[72:73], off
	global_load_dwordx4 v[176:179], v[66:67], off offset:128
	global_load_dwordx4 v[180:183], v[72:73], off offset:64
	global_load_dwordx4 v[184:187], v[68:69], off offset:128
	global_load_dwordx4 v[188:191], v[70:71], off offset:128
	global_load_dwordx4 v[192:195], v[66:67], off offset:192
	global_load_dwordx4 v[196:199], v[72:73], off offset:128
	global_load_dwordx4 v[200:203], v[68:69], off offset:192
	global_load_dwordx4 v[204:207], v[70:71], off offset:192
	global_load_dwordx4 v[220:223], v[72:73], off offset:192
	s_waitcnt vmcnt(15)
	v_mfma_f32_16x16x32_bf16 v[18:21], v[18:21], v[10:13], 0
	s_waitcnt vmcnt(13)
	v_mfma_f32_16x16x32_bf16 v[50:53], v[50:53], v[10:13], 0
	s_waitcnt vmcnt(12)
	v_mfma_f32_16x16x32_bf16 v[50:53], v[62:65], v[2:5], v[50:53]
	s_waitcnt vmcnt(11)
	v_mfma_f32_16x16x32_bf16 v[54:57], v[160:163], v[10:13], 0
	s_waitcnt vmcnt(14)
	v_mfma_f32_16x16x32_bf16 v[18:21], v[58:61], v[2:5], v[18:21]
	s_waitcnt vmcnt(10)
	v_mfma_f32_16x16x32_bf16 v[54:57], v[168:171], v[2:5], v[54:57]
	s_waitcnt vmcnt(9)
	v_mfma_f32_16x16x32_bf16 v[58:61], v[172:175], v[10:13], 0
	s_waitcnt vmcnt(8)
	v_mfma_f32_16x16x32_bf16 v[18:21], v[176:179], v[6:9], v[18:21]
	s_waitcnt vmcnt(7)
	v_mfma_f32_16x16x32_bf16 v[58:61], v[180:183], v[2:5], v[58:61]
	s_waitcnt vmcnt(6)
	v_mfma_f32_16x16x32_bf16 v[50:53], v[184:187], v[6:9], v[50:53]
	s_waitcnt vmcnt(5)
	v_mfma_f32_16x16x32_bf16 v[54:57], v[188:191], v[6:9], v[54:57]
	s_waitcnt vmcnt(4)
	v_mfma_f32_16x16x32_bf16 v[18:21], v[192:195], v[14:17], v[18:21]
	s_waitcnt vmcnt(3)
	v_mfma_f32_16x16x32_bf16 v[58:61], v[196:199], v[6:9], v[58:61]
	s_waitcnt vmcnt(2)
	v_mfma_f32_16x16x32_bf16 v[50:53], v[200:203], v[14:17], v[50:53]
	s_waitcnt vmcnt(1)
	v_mfma_f32_16x16x32_bf16 v[54:57], v[204:207], v[14:17], v[54:57]
	s_nop 7
	ds_write2st64_b32 v23, v18, v19 offset1:1
	ds_write2st64_b32 v23, v20, v21 offset0:2 offset1:3
	s_waitcnt vmcnt(0)
	v_mfma_f32_16x16x32_bf16 v[18:21], v[220:223], v[14:17], v[58:61]
	s_nop 3
	ds_write2st64_b32 v23, v50, v51 offset0:4 offset1:5
	ds_write2st64_b32 v23, v52, v53 offset0:6 offset1:7
	s_nop 0
	ds_write2st64_b32 v23, v54, v55 offset0:8 offset1:9
	ds_write2st64_b32 v23, v56, v57 offset0:10 offset1:11
	s_nop 2
	ds_write2st64_b32 v23, v18, v19 offset0:12 offset1:13
	ds_write2st64_b32 v23, v20, v21 offset0:14 offset1:15
	s_waitcnt lgkmcnt(0)
	s_barrier
	s_and_saveexec_b64 s[8:9], s[2:3]
	s_cbranch_execz .LBB0_238
	ds_read2st64_b32 v[18:19], v119 offset1:1
	ds_read2st64_b32 v[20:21], v119 offset0:16 offset1:17
	ds_read2st64_b32 v[50:51], v119 offset0:32 offset1:33
	ds_read2st64_b32 v[52:53], v119 offset0:48 offset1:49
	ds_read2st64_b32 v[54:55], v119 offset0:64 offset1:65
	ds_read2st64_b32 v[56:57], v119 offset0:80 offset1:81
	ds_read2st64_b32 v[58:59], v119 offset0:96 offset1:97
	ds_read2st64_b32 v[60:61], v119 offset0:112 offset1:113
	ds_read2st64_b32 v[62:63], v119 offset0:2 offset1:3
	ds_read2st64_b32 v[64:65], v119 offset0:4 offset1:5
	ds_read2st64_b32 v[66:67], v119 offset0:6 offset1:7
	s_waitcnt lgkmcnt(10)
	v_pk_add_f32 v[18:19], v[18:19], 0 op_sel_hi:[1,0]
	ds_read2st64_b32 v[68:69], v119 offset0:18 offset1:19
	ds_read2st64_b32 v[70:71], v119 offset0:20 offset1:21
	ds_read2st64_b32 v[72:73], v119 offset0:22 offset1:23
	s_waitcnt lgkmcnt(12)
	v_pk_add_f32 v[18:19], v[18:19], v[20:21]
	ds_read2st64_b32 v[20:21], v119 offset0:34 offset1:35
	ds_read2st64_b32 v[74:75], v119 offset0:36 offset1:37
	ds_read2st64_b32 v[76:77], v119 offset0:38 offset1:39
	s_waitcnt lgkmcnt(14)
	v_pk_add_f32 v[18:19], v[18:19], v[50:51]
	ds_read2st64_b32 v[50:51], v119 offset0:50 offset1:51
	ds_read2st64_b32 v[78:79], v119 offset0:52 offset1:53
	ds_read2st64_b32 v[80:81], v119 offset0:54 offset1:55
	s_waitcnt lgkmcnt(14)
	v_pk_add_f32 v[18:19], v[18:19], v[52:53]
	ds_read2st64_b32 v[52:53], v119 offset0:66 offset1:67
	ds_read2st64_b32 v[82:83], v119 offset0:68 offset1:69
	ds_read2st64_b32 v[84:85], v119 offset0:70 offset1:71
	v_pk_add_f32 v[18:19], v[18:19], v[54:55]
	ds_read2st64_b32 v[54:55], v119 offset0:82 offset1:83
	ds_read2st64_b32 v[86:87], v119 offset0:84 offset1:85
	ds_read2st64_b32 v[88:89], v119 offset0:86 offset1:87
	v_pk_add_f32 v[18:19], v[18:19], v[56:57]
	ds_read2st64_b32 v[56:57], v119 offset0:98 offset1:99
	ds_read2st64_b32 v[90:91], v119 offset0:100 offset1:101
	ds_read2st64_b32 v[92:93], v119 offset0:102 offset1:103
	s_waitcnt lgkmcnt(14)
	v_pk_add_f32 v[18:19], v[18:19], v[58:59]
	ds_read2st64_b32 v[58:59], v119 offset0:114 offset1:115
	ds_read2st64_b32 v[94:95], v119 offset0:116 offset1:117
	ds_read2st64_b32 v[96:97], v119 offset0:118 offset1:119
	v_pk_add_f32 v[18:19], v[18:19], v[60:61]
	v_pk_add_f32 v[60:61], v[62:63], 0 op_sel_hi:[1,0]
	s_cmpk_gt_i32 s6, 0x1ff
	v_pk_add_f32 v[60:61], v[60:61], v[68:69]
	s_mov_b64 s[10:11], -1
	v_pk_add_f32 v[20:21], v[60:61], v[20:21]
	s_waitcnt lgkmcnt(14)
; __device__ __forceinline__ unsigned short f2bf(float f) { return (unsigned short)(cvt_pk_bf16(f, f) & 0xffffu); }
;   __device__ __forceinline__ void group(int row, int c32, int fq, f32x4 v0, f32x4 v1) const {
;     ...
;     else if (c32 < 1920) { const int cc = c32 - 1792, g = cc >> 6; bf16_t* p = vts + ((size_t)(b * 2 + g) * 64 + (cc & 63) + fq * 4) * E + e;
; #pragma unroll
;       for (int j = 0; j < 4; ++j) { p[(size_t)j * E] = f2bf(v0[j]); p[(size_t)(j + 16) * E] = f2bf(v1[j]); } }
; template <class Epi, class Pre>
; __device__ __forceinline__ void meta_gemm(const bf16_t* __restrict__ A, int lda, const bf16_t* __restrict__ Bt, int ldb, int N, int K, Epi& epi, Pre pre) {
;     ...
;           for (int j = 0; j < 4; ++j) { float s = 0.f;
; #pragma unroll
;             for (int w = 0; w < 8; ++w) s += part[(w * 16 + (bj * 2 + n) * 4 + j) * 64 + lane];
;             v[bj][n][j] = s; }
;       pre(fr, fq);
;       epi(NREAL + 16 * wid + fr, cb, fq, v[0][0], v[0][1], v[1][0], v[1][1]);
	v_pk_add_f32 v[20:21], v[20:21], v[50:51]
	v_pk_add_f32 v[50:51], v[64:65], 0 op_sel_hi:[1,0]
	s_waitcnt lgkmcnt(11)
	v_pk_add_f32 v[20:21], v[20:21], v[52:53]
	v_pk_add_f32 v[50:51], v[50:51], v[70:71]
	s_waitcnt lgkmcnt(8)
	v_pk_add_f32 v[20:21], v[20:21], v[54:55]
	v_pk_add_f32 v[50:51], v[50:51], v[74:75]
	s_waitcnt lgkmcnt(5)
	v_pk_add_f32 v[20:21], v[20:21], v[56:57]
	v_pk_add_f32 v[50:51], v[50:51], v[78:79]
	s_waitcnt lgkmcnt(2)
	v_pk_add_f32 v[20:21], v[20:21], v[58:59]
	v_pk_add_f32 v[50:51], v[50:51], v[82:83]
	s_nop 0
	v_pk_add_f32 v[50:51], v[50:51], v[86:87]
	s_nop 0
	v_pk_add_f32 v[50:51], v[50:51], v[90:91]
	s_waitcnt lgkmcnt(1)
	v_pk_add_f32 v[56:57], v[50:51], v[94:95]
	v_pk_add_f32 v[50:51], v[66:67], 0 op_sel_hi:[1,0]
	s_nop 0
	v_pk_add_f32 v[50:51], v[50:51], v[72:73]
	s_nop 0
	v_pk_add_f32 v[50:51], v[50:51], v[76:77]
	s_nop 0
	v_pk_add_f32 v[50:51], v[50:51], v[80:81]
	s_nop 0
	v_pk_add_f32 v[50:51], v[50:51], v[84:85]
	s_nop 0
	v_pk_add_f32 v[50:51], v[50:51], v[88:89]
	s_nop 0
	v_pk_add_f32 v[50:51], v[50:51], v[92:93]
	s_waitcnt lgkmcnt(0)
	v_pk_add_f32 v[68:69], v[50:51], v[96:97]
	ds_read2st64_b32 v[54:55], v119 offset0:8 offset1:9
	ds_read2st64_b32 v[52:53], v119 offset0:24 offset1:25
	ds_read2st64_b32 v[50:51], v119 offset0:10 offset1:11
	ds_read2st64_b32 v[124:125], v119 offset0:12 offset1:13
	ds_read2st64_b32 v[126:127], v119 offset0:14 offset1:15
	ds_read2st64_b32 v[58:59], v119 offset0:26 offset1:27
	ds_read2st64_b32 v[128:129], v119 offset0:28 offset1:29
	ds_read2st64_b32 v[130:131], v119 offset0:30 offset1:31
	ds_read2st64_b32 v[106:107], v119 offset0:40 offset1:41
	ds_read2st64_b32 v[102:103], v119 offset0:56 offset1:57
	ds_read2st64_b32 v[60:61], v119 offset0:42 offset1:43
	ds_read2st64_b32 v[132:133], v119 offset0:44 offset1:45
	ds_read2st64_b32 v[134:135], v119 offset0:46 offset1:47
	ds_read2st64_b32 v[62:63], v119 offset0:58 offset1:59
	ds_read2st64_b32 v[136:137], v119 offset0:60 offset1:61
	ds_read2st64_b32 v[138:139], v119 offset0:62 offset1:63
	ds_read2st64_b32 v[112:113], v119 offset0:72 offset1:73
	ds_read2st64_b32 v[110:111], v119 offset0:88 offset1:89
	ds_read2st64_b32 v[66:67], v119 offset0:74 offset1:75
	ds_read2st64_b32 v[140:141], v119 offset0:76 offset1:77
	ds_read2st64_b32 v[142:143], v119 offset0:78 offset1:79
	ds_read2st64_b32 v[72:73], v119 offset0:90 offset1:91
	ds_read2st64_b32 v[144:145], v119 offset0:92 offset1:93
	ds_read2st64_b32 v[146:147], v119 offset0:94 offset1:95
	ds_read2st64_b32 v[116:117], v119 offset0:104 offset1:105
	ds_read2st64_b32 v[114:115], v119 offset0:120 offset1:121
	ds_read2st64_b32 v[80:81], v119 offset0:106 offset1:107
	ds_read2st64_b32 v[148:149], v119 offset0:108 offset1:109
	ds_read2st64_b32 v[150:151], v119 offset0:110 offset1:111
	ds_read2st64_b32 v[84:85], v119 offset0:122 offset1:123
	ds_read2st64_b32 v[152:153], v119 offset0:124 offset1:125
	ds_read2st64_b32 v[158:159], v119 offset0:126 offset1:127
	s_waitcnt lgkmcnt(14)
	v_mov_b32_e32 v89, v55
	v_mov_b32_e32 v93, v53
	v_mov_b32_e32 v95, v107
	v_mov_b32_e32 v97, v103
	v_mov_b32_e32 v99, v113
	v_mov_b32_e32 v101, v111
	s_waitcnt lgkmcnt(7)
	v_mov_b32_e32 v105, v117
	s_waitcnt lgkmcnt(6)
	v_mov_b32_e32 v109, v115
	v_mov_b32_e32 v91, v51
	v_mov_b32_e32 v87, v59
	v_mov_b32_e32 v83, v61
	v_mov_b32_e32 v79, v63
	v_mov_b32_e32 v77, v67
	v_mov_b32_e32 v75, v73
	s_waitcnt lgkmcnt(5)
	v_mov_b32_e32 v71, v81
	s_waitcnt lgkmcnt(2)
	v_mov_b32_e32 v65, v85
	v_mov_b32_e32 v88, v124
	v_mov_b32_e32 v55, v125
	v_mov_b32_e32 v92, v128
	v_mov_b32_e32 v53, v129
	v_mov_b32_e32 v94, v132
	v_mov_b32_e32 v107, v133
	v_mov_b32_e32 v96, v136
	v_mov_b32_e32 v103, v137
	v_mov_b32_e32 v98, v140
	v_mov_b32_e32 v113, v141
	v_mov_b32_e32 v100, v144
	v_mov_b32_e32 v111, v145
	v_mov_b32_e32 v104, v148
	v_mov_b32_e32 v117, v149
	s_waitcnt lgkmcnt(1)
	v_mov_b32_e32 v108, v152
	v_mov_b32_e32 v115, v153
	v_mov_b32_e32 v90, v126
	v_mov_b32_e32 v51, v127
	v_mov_b32_e32 v86, v130
	v_mov_b32_e32 v59, v131
	v_mov_b32_e32 v82, v134
	v_mov_b32_e32 v61, v135
	v_mov_b32_e32 v78, v138
	v_mov_b32_e32 v63, v139
	v_mov_b32_e32 v76, v142
	v_mov_b32_e32 v67, v143
	v_mov_b32_e32 v74, v146
	v_mov_b32_e32 v73, v147
	v_mov_b32_e32 v70, v150
	v_mov_b32_e32 v81, v151
	s_waitcnt lgkmcnt(0)
	v_mov_b32_e32 v64, v158
	v_mov_b32_e32 v85, v159
	s_cbranch_scc0 .LBB0_262
	s_cmpk_gt_u32 s0, 0x2ff
	s_cbranch_scc0 .LBB0_259
	s_cmpk_gt_u32 s0, 0x3ff
	s_cbranch_scc0 .LBB0_256
	s_cmpk_gt_u32 s0, 0x4ff
	s_cbranch_scc0 .LBB0_253
	s_cmpk_gt_u32 s7, 0x67f
	s_cbranch_scc0 .LBB0_250
	s_cmpk_gt_u32 s0, 0x6ff
	s_cbranch_scc0 .LBB0_247
	s_add_i32 s7, s6, 0xfffff900
	s_lshr_b32 s7, s7, 6
	v_add_u32_e32 v124, s7, v120
	v_ashrrev_i32_e32 v125, 31, v124
	v_lshlrev_b64 v[124:125], 6, v[124:125]
	s_and_b32 s7, s1, 32
	v_or3_b32 v0, s7, v121, v124
	v_mad_u64_u32 v[126:127], s[10:11], v0, s95, v[28:29]
	s_mov_b32 s7, 0x40000
	v_mad_i32_i24 v127, v125, s95, v127
	v_cvt_pk_bf16_f32 v0, v18, s0
	v_add_co_u32_e32 v124, vcc, s7, v126
	global_store_short v[126:127], v0, off
	v_cvt_pk_bf16_f32 v0, v56, s0
	v_addc_co_u32_e32 v125, vcc, 0, v127, vcc
	s_movk_i32 s7, 0x4000
	global_store_short v[124:125], v0, off offset:2048
	v_add_co_u32_e32 v124, vcc, s7, v126
	v_cvt_pk_bf16_f32 v0, v19, s0
	s_nop 0
	v_addc_co_u32_e32 v125, vcc, 0, v127, vcc
	s_mov_b32 s7, 0x44000
	global_store_short v[124:125], v0, off offset:128
	v_add_co_u32_e32 v124, vcc, s7, v126
	v_cvt_pk_bf16_f32 v0, v57, s0
	s_nop 0
	v_addc_co_u32_e32 v125, vcc, 0, v127, vcc
	s_mov_b32 s7, 0x8000
	global_store_short v[124:125], v0, off offset:2176
	v_add_co_u32_e32 v124, vcc, s7, v126
	v_cvt_pk_bf16_f32 v0, v20, s0
	s_nop 0
	v_addc_co_u32_e32 v125, vcc, 0, v127, vcc
	s_mov_b32 s7, 0x48000
	global_store_short v[124:125], v0, off offset:256
	v_add_co_u32_e32 v124, vcc, s7, v126
	v_cvt_pk_bf16_f32 v0, v68, s0
	s_nop 0
	v_addc_co_u32_e32 v125, vcc, 0, v127, vcc
	global_store_short v[124:125], v0, off offset:2304
	v_add_co_u32_e32 v124, vcc, 0xc000, v126
	v_cvt_pk_bf16_f32 v0, v21, s0
	s_nop 0
	v_addc_co_u32_e32 v125, vcc, 0, v127, vcc
	global_store_short v[124:125], v0, off offset:384
	v_add_co_u32_e32 v124, vcc, 0x4c000, v126
	v_cvt_pk_bf16_f32 v0, v69, s0
	s_nop 0
	v_addc_co_u32_e32 v125, vcc, 0, v127, vcc
	global_store_short v[124:125], v0, off offset:2432
	s_mov_b64 s[10:11], 0

; template <class Epi, class Pre>
; __device__ __forceinline__ void meta_gemm(const bf16_t* __restrict__ A, int lda, const bf16_t* __restrict__ Bt, int ldb, int N, int K, Epi& epi, Pre pre) {
;     ...
;     const bf16_t* ap = A + (size_t)(NREAL + fr) * lda + wid * ks + fq * 8;
;     const bf16_t* bp = Bt + (size_t)(cb + fr) * ldb + wid * ks + fq * 8;
; #pragma unroll 4
;     for (int k0 = 0; k0 < ks; k0 += 32) {
;       const bf16x8 a = *(const bf16x8*)(ap + k0);
; #pragma unroll
;       for (int bj = 0; bj < 2; ++bj)
; #pragma unroll
;         for (int n = 0; n < 2; ++n) { const bf16x8 b = *(const bf16x8*)(bp + (size_t)(bj * 128 + n * 16) * ldb + k0); acc[bj][n] = __builtin_amdgcn_mfma_f32_16x16x32_bf16(b, a, acc[bj][n], 0, 0, 0); }
;     }
; #pragma unroll
;     for (int bj = 0; bj < 2; ++bj)
; #pragma unroll
;       for (int n = 0; n < 2; ++n)
; #pragma unroll
;         for (int j = 0; j < 4; ++j) part[(wid * 16 + (bj * 2 + n) * 4 + j) * 64 + lane] = acc[bj][n][j];
;     __syncthreads();
.LBB0_1446:
	s_and_b32 s10, s1, 0x60
	s_and_b32 s11, s0, 0xffffff00
	s_or_b32 s12, s11, s10
	v_or_b32_e32 v2, s12, v0
	v_ashrrev_i32_e32 v3, 31, v2
	v_lshlrev_b64 v[2:3], 11, v[2:3]
	v_lshl_add_u64 v[32:33], v[20:21], 0, v[2:3]
	s_mov_b32 s10, 0x8000
	v_add_co_u32_e32 v34, vcc, s10, v32
	s_mov_b32 s10, 0x40000
	s_nop 0
	v_addc_co_u32_e32 v35, vcc, 0, v33, vcc
	v_add_co_u32_e32 v36, vcc, s10, v32
	s_mov_b32 s10, 0x48000
	s_nop 0
	v_addc_co_u32_e32 v37, vcc, 0, v33, vcc
	v_add_co_u32_e32 v38, vcc, s10, v32
	global_load_dwordx4 v[2:5], v[18:19], off
	global_load_dwordx4 v[6:9], v[32:33], off
	v_addc_co_u32_e32 v39, vcc, 0, v33, vcc
	global_load_dwordx4 v[10:13], v[34:35], off
	global_load_dwordx4 v[14:17], v[36:37], off
	global_load_dwordx4 v[24:27], v[38:39], off
	global_load_dwordx4 v[54:57], v[18:19], off offset:64
	global_load_dwordx4 v[58:61], v[32:33], off offset:64
	global_load_dwordx4 v[62:65], v[34:35], off offset:64
	global_load_dwordx4 v[66:69], v[36:37], off offset:64
	global_load_dwordx4 v[70:73], v[38:39], off offset:64
	global_load_dwordx4 v[74:77], v[18:19], off offset:128
	global_load_dwordx4 v[78:81], v[32:33], off offset:128
	global_load_dwordx4 v[82:85], v[34:35], off offset:128
	global_load_dwordx4 v[86:89], v[36:37], off offset:128
	global_load_dwordx4 v[90:93], v[38:39], off offset:128
	global_load_dwordx4 v[94:97], v[18:19], off offset:192
	global_load_dwordx4 v[98:101], v[32:33], off offset:192
	global_load_dwordx4 v[102:105], v[34:35], off offset:192
	global_load_dwordx4 v[106:109], v[36:37], off offset:192
	global_load_dwordx4 v[110:113], v[38:39], off offset:192
	s_waitcnt vmcnt(18)
	v_mfma_f32_16x16x32_bf16 v[6:9], v[6:9], v[2:5], 0
	s_waitcnt vmcnt(17)
	v_mfma_f32_16x16x32_bf16 v[10:13], v[10:13], v[2:5], 0
	s_waitcnt vmcnt(16)
	v_mfma_f32_16x16x32_bf16 v[14:17], v[14:17], v[2:5], 0
	s_waitcnt vmcnt(15)
	v_mfma_f32_16x16x32_bf16 v[2:5], v[24:27], v[2:5], 0
	s_waitcnt vmcnt(13)
	v_mfma_f32_16x16x32_bf16 v[6:9], v[58:61], v[54:57], v[6:9]
	s_waitcnt vmcnt(12)
	v_mfma_f32_16x16x32_bf16 v[10:13], v[62:65], v[54:57], v[10:13]
	s_waitcnt vmcnt(11)
	v_mfma_f32_16x16x32_bf16 v[14:17], v[66:69], v[54:57], v[14:17]
	s_waitcnt vmcnt(10)
	v_mfma_f32_16x16x32_bf16 v[2:5], v[70:73], v[54:57], v[2:5]
	s_waitcnt vmcnt(8)
	v_mfma_f32_16x16x32_bf16 v[6:9], v[78:81], v[74:77], v[6:9]
	s_waitcnt vmcnt(7)
	v_mfma_f32_16x16x32_bf16 v[10:13], v[82:85], v[74:77], v[10:13]
	s_waitcnt vmcnt(6)
	v_mfma_f32_16x16x32_bf16 v[14:17], v[86:89], v[74:77], v[14:17]
	s_waitcnt vmcnt(5)
	v_mfma_f32_16x16x32_bf16 v[2:5], v[90:93], v[74:77], v[2:5]
	s_waitcnt vmcnt(3)
	v_mfma_f32_16x16x32_bf16 v[6:9], v[98:101], v[94:97], v[6:9]
	s_waitcnt vmcnt(2)
	v_mfma_f32_16x16x32_bf16 v[10:13], v[102:105], v[94:97], v[10:13]
	s_waitcnt vmcnt(1)
	v_mfma_f32_16x16x32_bf16 v[14:17], v[106:109], v[94:97], v[14:17]
	s_waitcnt vmcnt(0)
	v_mfma_f32_16x16x32_bf16 v[2:5], v[110:113], v[94:97], v[2:5]
	s_nop 3
	ds_write2st64_b32 v43, v6, v7 offset1:1
	ds_write2st64_b32 v43, v8, v9 offset0:2 offset1:3
	ds_write2st64_b32 v43, v10, v11 offset0:4 offset1:5
	ds_write2st64_b32 v43, v12, v13 offset0:6 offset1:7
	s_nop 0
	ds_write2st64_b32 v43, v14, v15 offset0:8 offset1:9
	ds_write2st64_b32 v43, v16, v17 offset0:10 offset1:11
	s_nop 0
	ds_write2st64_b32 v43, v2, v3 offset0:12 offset1:13
	ds_write2st64_b32 v43, v4, v5 offset0:14 offset1:15
	s_waitcnt lgkmcnt(0)
	s_barrier
	s_and_saveexec_b64 s[10:11], s[4:5]
	s_cbranch_execz .LBB0_1445
	ds_read2st64_b32 v[2:3], v42 offset1:1
	ds_read2st64_b32 v[4:5], v42 offset0:16 offset1:17
	ds_read2st64_b32 v[6:7], v42 offset0:32 offset1:33
	ds_read2st64_b32 v[8:9], v42 offset0:48 offset1:49
	ds_read2st64_b32 v[10:11], v42 offset0:64 offset1:65
	ds_read2st64_b32 v[12:13], v42 offset0:80 offset1:81
	ds_read2st64_b32 v[14:15], v42 offset0:96 offset1:97
	ds_read2st64_b32 v[16:17], v42 offset0:112 offset1:113
	ds_read2st64_b32 v[24:25], v42 offset0:2 offset1:3
	ds_read2st64_b32 v[26:27], v42 offset0:18 offset1:19
	ds_read2st64_b32 v[28:29], v42 offset0:34 offset1:35
	ds_read2st64_b32 v[30:31], v42 offset0:50 offset1:51
	ds_read2st64_b32 v[32:33], v42 offset0:66 offset1:67
	ds_read2st64_b32 v[34:35], v42 offset0:82 offset1:83
	ds_read2st64_b32 v[36:37], v42 offset0:98 offset1:99
	ds_read2st64_b32 v[38:39], v42 offset0:114 offset1:115
	s_waitcnt lgkmcnt(7)
	v_pk_add_f32 v[24:25], v[24:25], 0 op_sel_hi:[1,0]
	v_pk_add_f32 v[2:3], v[2:3], 0 op_sel_hi:[1,0]
	s_ashr_i32 s13, s12, 31
	v_pk_add_f32 v[2:3], v[2:3], v[4:5]
	s_waitcnt lgkmcnt(6)
	v_pk_add_f32 v[4:5], v[24:25], v[26:27]
	v_pk_add_f32 v[2:3], v[2:3], v[6:7]
	s_waitcnt lgkmcnt(5)
	v_pk_add_f32 v[4:5], v[4:5], v[28:29]
	v_pk_add_f32 v[2:3], v[2:3], v[8:9]
	s_waitcnt lgkmcnt(4)
	v_pk_add_f32 v[4:5], v[4:5], v[30:31]
	v_pk_add_f32 v[2:3], v[2:3], v[10:11]
	s_waitcnt lgkmcnt(3)
	v_pk_add_f32 v[4:5], v[4:5], v[32:33]
	v_pk_add_f32 v[2:3], v[2:3], v[12:13]
	s_waitcnt lgkmcnt(2)
	v_pk_add_f32 v[4:5], v[4:5], v[34:35]
	v_pk_add_f32 v[2:3], v[2:3], v[14:15]
	s_waitcnt lgkmcnt(1)
	v_pk_add_f32 v[4:5], v[4:5], v[36:37]
	v_pk_add_f32 v[24:25], v[2:3], v[16:17]
	s_waitcnt lgkmcnt(0)
; template <class Epi, class Pre>
; __device__ __forceinline__ void meta_gemm(const bf16_t* __restrict__ A, int lda, const bf16_t* __restrict__ Bt, int ldb, int N, int K, Epi& epi, Pre pre) {
;     ...
;           for (int j = 0; j < 4; ++j) { float s = 0.f;
; #pragma unroll
;             for (int w = 0; w < 8; ++w) s += part[(w * 16 + (bj * 2 + n) * 4 + j) * 64 + lane];
;             v[bj][n][j] = s; }
;       pre(fr, fq);
;       epi(NREAL + 16 * wid + fr, cb, fq, v[0][0], v[0][1], v[1][0], v[1][1]);
	v_pk_add_f32 v[26:27], v[4:5], v[38:39]
	ds_read2st64_b32 v[2:3], v42 offset0:4 offset1:5
	ds_read2st64_b32 v[4:5], v42 offset0:20 offset1:21
	ds_read2st64_b32 v[6:7], v42 offset0:36 offset1:37
	ds_read2st64_b32 v[8:9], v42 offset0:52 offset1:53
	ds_read2st64_b32 v[10:11], v42 offset0:68 offset1:69
	ds_read2st64_b32 v[12:13], v42 offset0:84 offset1:85
	ds_read2st64_b32 v[14:15], v42 offset0:100 offset1:101
	ds_read2st64_b32 v[16:17], v42 offset0:116 offset1:117
	ds_read2st64_b32 v[28:29], v42 offset0:6 offset1:7
	ds_read2st64_b32 v[30:31], v42 offset0:22 offset1:23
	ds_read2st64_b32 v[32:33], v42 offset0:38 offset1:39
	ds_read2st64_b32 v[34:35], v42 offset0:54 offset1:55
	ds_read2st64_b32 v[36:37], v42 offset0:70 offset1:71
	ds_read2st64_b32 v[38:39], v42 offset0:86 offset1:87
	ds_read2st64_b32 v[40:41], v42 offset0:102 offset1:103
	ds_read2st64_b32 v[44:45], v42 offset0:118 offset1:119
	s_waitcnt lgkmcnt(7)
	v_pk_add_f32 v[28:29], v[28:29], 0 op_sel_hi:[1,0]
	v_pk_add_f32 v[2:3], v[2:3], 0 op_sel_hi:[1,0]
	s_nop 0
	v_pk_add_f32 v[2:3], v[2:3], v[4:5]
	s_waitcnt lgkmcnt(6)
	v_pk_add_f32 v[4:5], v[28:29], v[30:31]
	v_pk_add_f32 v[2:3], v[2:3], v[6:7]
	s_waitcnt lgkmcnt(5)
	v_pk_add_f32 v[4:5], v[4:5], v[32:33]
	v_pk_add_f32 v[2:3], v[2:3], v[8:9]
	s_waitcnt lgkmcnt(4)
	v_pk_add_f32 v[4:5], v[4:5], v[34:35]
	v_pk_add_f32 v[2:3], v[2:3], v[10:11]
	s_waitcnt lgkmcnt(3)
	v_pk_add_f32 v[4:5], v[4:5], v[36:37]
	v_pk_add_f32 v[2:3], v[2:3], v[12:13]
	s_waitcnt lgkmcnt(2)
	v_pk_add_f32 v[4:5], v[4:5], v[38:39]
	v_pk_add_f32 v[2:3], v[2:3], v[14:15]
	s_waitcnt lgkmcnt(1)
	v_pk_add_f32 v[4:5], v[4:5], v[40:41]
	v_pk_add_f32 v[28:29], v[2:3], v[16:17]
	s_waitcnt lgkmcnt(0)
	v_pk_add_f32 v[30:31], v[4:5], v[44:45]
	ds_read2st64_b32 v[2:3], v42 offset0:8 offset1:9
	ds_read2st64_b32 v[4:5], v42 offset0:24 offset1:25
	ds_read2st64_b32 v[6:7], v42 offset0:40 offset1:41
	ds_read2st64_b32 v[8:9], v42 offset0:56 offset1:57
	ds_read2st64_b32 v[10:11], v42 offset0:72 offset1:73
	ds_read2st64_b32 v[12:13], v42 offset0:88 offset1:89
	ds_read2st64_b32 v[14:15], v42 offset0:104 offset1:105
	ds_read2st64_b32 v[16:17], v42 offset0:120 offset1:121
	ds_read2st64_b32 v[32:33], v42 offset0:10 offset1:11
	ds_read2st64_b32 v[34:35], v42 offset0:26 offset1:27
	ds_read2st64_b32 v[36:37], v42 offset0:42 offset1:43
	ds_read2st64_b32 v[38:39], v42 offset0:58 offset1:59
	ds_read2st64_b32 v[40:41], v42 offset0:74 offset1:75
	ds_read2st64_b32 v[44:45], v42 offset0:90 offset1:91
	ds_read2st64_b32 v[46:47], v42 offset0:106 offset1:107
	ds_read2st64_b32 v[48:49], v42 offset0:122 offset1:123
	s_waitcnt lgkmcnt(7)
	v_pk_add_f32 v[32:33], v[32:33], 0 op_sel_hi:[1,0]
	v_pk_add_f32 v[2:3], v[2:3], 0 op_sel_hi:[1,0]
	s_nop 0
	v_pk_add_f32 v[2:3], v[2:3], v[4:5]
	s_waitcnt lgkmcnt(6)
	v_pk_add_f32 v[4:5], v[32:33], v[34:35]
	v_pk_add_f32 v[2:3], v[2:3], v[6:7]
	s_waitcnt lgkmcnt(5)
	v_pk_add_f32 v[4:5], v[4:5], v[36:37]
	v_pk_add_f32 v[2:3], v[2:3], v[8:9]
	s_waitcnt lgkmcnt(4)
	v_pk_add_f32 v[4:5], v[4:5], v[38:39]
	v_pk_add_f32 v[2:3], v[2:3], v[10:11]
	s_waitcnt lgkmcnt(3)
	v_pk_add_f32 v[4:5], v[4:5], v[40:41]
	v_pk_add_f32 v[2:3], v[2:3], v[12:13]
	s_waitcnt lgkmcnt(2)
	v_pk_add_f32 v[4:5], v[4:5], v[44:45]
	v_pk_add_f32 v[2:3], v[2:3], v[14:15]
	s_waitcnt lgkmcnt(1)
	v_pk_add_f32 v[4:5], v[4:5], v[46:47]
	v_pk_add_f32 v[32:33], v[2:3], v[16:17]
	s_waitcnt lgkmcnt(0)
	v_pk_add_f32 v[34:35], v[4:5], v[48:49]
	ds_read2st64_b32 v[2:3], v42 offset0:12 offset1:13
	ds_read2st64_b32 v[4:5], v42 offset0:28 offset1:29
	ds_read2st64_b32 v[6:7], v42 offset0:44 offset1:45
	ds_read2st64_b32 v[8:9], v42 offset0:60 offset1:61
	ds_read2st64_b32 v[10:11], v42 offset0:76 offset1:77
	ds_read2st64_b32 v[12:13], v42 offset0:92 offset1:93
	ds_read2st64_b32 v[14:15], v42 offset0:108 offset1:109
	ds_read2st64_b32 v[16:17], v42 offset0:124 offset1:125
	ds_read2st64_b32 v[36:37], v42 offset0:14 offset1:15
	ds_read2st64_b32 v[38:39], v42 offset0:30 offset1:31
	ds_read2st64_b32 v[40:41], v42 offset0:46 offset1:47
	ds_read2st64_b32 v[44:45], v42 offset0:62 offset1:63
	ds_read2st64_b32 v[46:47], v42 offset0:78 offset1:79
	ds_read2st64_b32 v[48:49], v42 offset0:94 offset1:95
	ds_read2st64_b32 v[50:51], v42 offset0:110 offset1:111
	ds_read2st64_b32 v[52:53], v42 offset0:126 offset1:127
	s_waitcnt lgkmcnt(7)
	v_pk_add_f32 v[36:37], v[36:37], 0 op_sel_hi:[1,0]
	v_pk_add_f32 v[2:3], v[2:3], 0 op_sel_hi:[1,0]
	s_nop 0
	v_pk_add_f32 v[2:3], v[2:3], v[4:5]
	s_waitcnt lgkmcnt(6)
	v_pk_add_f32 v[4:5], v[36:37], v[38:39]
	v_pk_add_f32 v[2:3], v[2:3], v[6:7]
	s_waitcnt lgkmcnt(5)
	v_pk_add_f32 v[4:5], v[4:5], v[40:41]
	v_pk_add_f32 v[2:3], v[2:3], v[8:9]
	s_waitcnt lgkmcnt(4)
	v_pk_add_f32 v[4:5], v[4:5], v[44:45]
	v_pk_add_f32 v[2:3], v[2:3], v[10:11]
	s_waitcnt lgkmcnt(3)
	v_pk_add_f32 v[4:5], v[4:5], v[46:47]
	v_pk_add_f32 v[2:3], v[2:3], v[12:13]
	s_waitcnt lgkmcnt(2)
	v_pk_add_f32 v[4:5], v[4:5], v[48:49]
	v_pk_add_f32 v[2:3], v[2:3], v[14:15]
	s_waitcnt lgkmcnt(1)
	v_pk_add_f32 v[4:5], v[4:5], v[50:51]
	v_lshl_add_u64 v[40:41], s[12:13], 2, v[22:23]
	v_pk_add_f32 v[36:37], v[2:3], v[16:17]
	s_waitcnt lgkmcnt(0)
	v_pk_add_f32 v[38:39], v[4:5], v[52:53]
	global_load_dwordx4 v[2:5], v[40:41], off
	global_load_dwordx4 v[6:9], v[40:41], off offset:64
	global_load_dwordx4 v[10:13], v[40:41], off offset:512
	global_load_dwordx4 v[14:17], v[40:41], off offset:576
	s_waitcnt vmcnt(3)
	v_pk_add_f32 v[4:5], v[26:27], v[4:5]
	v_pk_add_f32 v[2:3], v[24:25], v[2:3]
	global_store_dwordx4 v[40:41], v[2:5], off
	s_waitcnt vmcnt(3)
	s_nop 0
	v_pk_add_f32 v[4:5], v[30:31], v[8:9]
	v_pk_add_f32 v[2:3], v[28:29], v[6:7]
	global_store_dwordx4 v[40:41], v[2:5], off offset:64
	s_waitcnt vmcnt(3)
	s_nop 0
	v_pk_add_f32 v[4:5], v[34:35], v[12:13]
	v_pk_add_f32 v[2:3], v[32:33], v[10:11]
	global_store_dwordx4 v[40:41], v[2:5], off offset:512
	s_waitcnt vmcnt(3)
	s_nop 0
	v_pk_add_f32 v[4:5], v[38:39], v[16:17]
	v_pk_add_f32 v[2:3], v[36:37], v[14:15]
	global_store_dwordx4 v[40:41], v[2:5], off offset:576
	s_branch .LBB0_1445

; template <class Epi, class Pre>
; __device__ __forceinline__ void meta_gemm(const bf16_t* __restrict__ A, int lda, const bf16_t* __restrict__ Bt, int ldb, int N, int K, Epi& epi, Pre pre) {
;     ...
;     const bf16_t* ap = A + (size_t)(NREAL + fr) * lda + wid * ks + fq * 8;
;     const bf16_t* bp = Bt + (size_t)(cb + fr) * ldb + wid * ks + fq * 8;
; #pragma unroll 4
;     for (int k0 = 0; k0 < ks; k0 += 32) {
;       const bf16x8 a = *(const bf16x8*)(ap + k0);
; #pragma unroll
;       for (int bj = 0; bj < 2; ++bj)
; #pragma unroll
;         for (int n = 0; n < 2; ++n) { const bf16x8 b = *(const bf16x8*)(bp + (size_t)(bj * 128 + n * 16) * ldb + k0); acc[bj][n] = __builtin_amdgcn_mfma_f32_16x16x32_bf16(b, a, acc[bj][n], 0, 0, 0); }
;     }
; #pragma unroll
;     for (int bj = 0; bj < 2; ++bj)
; #pragma unroll
;       for (int n = 0; n < 2; ++n)
; #pragma unroll
;         for (int j = 0; j < 4; ++j) part[(wid * 16 + (bj * 2 + n) * 4 + j) * 64 + lane] = acc[bj][n][j];
;     __syncthreads();
.LBB0_1470:
	s_and_b32 s6, s1, 0x60
	s_and_b32 s7, s0, 0xffffff00
	s_or_b32 s8, s7, s6
	v_or_b32_e32 v18, s8, v0
	v_ashrrev_i32_e32 v19, 31, v18
	v_lshlrev_b64 v[18:19], 11, v[18:19]
	v_lshl_add_u64 v[44:45], v[34:35], 0, v[18:19]
	global_load_dwordx4 v[18:21], v[44:45], off
	global_load_dwordx4 v[40:43], v[44:45], off offset:64
	v_add_co_u32_e32 v46, vcc, 0x8000, v44
	v_addc_co_u32_e32 v47, vcc, 0, v45, vcc
	v_add_co_u32_e32 v48, vcc, 0x40000, v44
	v_addc_co_u32_e32 v49, vcc, 0, v45, vcc
	v_add_co_u32_e32 v50, vcc, 0x48000, v44
	v_addc_co_u32_e32 v51, vcc, 0, v45, vcc
	global_load_dwordx4 v[160:163], v[46:47], off
	global_load_dwordx4 v[168:171], v[46:47], off offset:64
	global_load_dwordx4 v[172:175], v[48:49], off
	global_load_dwordx4 v[176:179], v[48:49], off offset:64
	global_load_dwordx4 v[180:183], v[50:51], off
	global_load_dwordx4 v[184:187], v[50:51], off offset:64
	global_load_dwordx4 v[188:191], v[44:45], off offset:128
	global_load_dwordx4 v[192:195], v[46:47], off offset:128
	global_load_dwordx4 v[196:199], v[48:49], off offset:128
	global_load_dwordx4 v[200:203], v[50:51], off offset:128
	global_load_dwordx4 v[204:207], v[44:45], off offset:192
	global_load_dwordx4 v[220:223], v[46:47], off offset:192
	global_load_dwordx4 v[224:227], v[48:49], off offset:192
	global_load_dwordx4 v[248:251], v[50:51], off offset:192
	s_waitcnt vmcnt(15)
	v_mfma_f32_16x16x32_bf16 v[18:21], v[18:21], v[10:13], 0
	s_waitcnt vmcnt(14)
	v_mfma_f32_16x16x32_bf16 v[18:21], v[40:43], v[2:5], v[18:21]
	s_waitcnt vmcnt(13)
	v_mfma_f32_16x16x32_bf16 v[22:25], v[160:163], v[10:13], 0
	s_waitcnt vmcnt(12)
	v_mfma_f32_16x16x32_bf16 v[22:25], v[168:171], v[2:5], v[22:25]
	s_waitcnt vmcnt(11)
	v_mfma_f32_16x16x32_bf16 v[26:29], v[172:175], v[10:13], 0
	s_waitcnt vmcnt(10)
	v_mfma_f32_16x16x32_bf16 v[26:29], v[176:179], v[2:5], v[26:29]
	s_waitcnt vmcnt(9)
	v_mfma_f32_16x16x32_bf16 v[30:33], v[180:183], v[10:13], 0
	s_waitcnt vmcnt(8)
	v_mfma_f32_16x16x32_bf16 v[30:33], v[184:187], v[2:5], v[30:33]
	s_waitcnt vmcnt(7)
	v_mfma_f32_16x16x32_bf16 v[18:21], v[188:191], v[6:9], v[18:21]
	s_waitcnt vmcnt(6)
	v_mfma_f32_16x16x32_bf16 v[22:25], v[192:195], v[6:9], v[22:25]
	s_waitcnt vmcnt(5)
	v_mfma_f32_16x16x32_bf16 v[26:29], v[196:199], v[6:9], v[26:29]
	s_waitcnt vmcnt(4)
	v_mfma_f32_16x16x32_bf16 v[30:33], v[200:203], v[6:9], v[30:33]
	s_waitcnt vmcnt(3)
	v_mfma_f32_16x16x32_bf16 v[18:21], v[204:207], v[14:17], v[18:21]
	s_waitcnt vmcnt(2)
	v_mfma_f32_16x16x32_bf16 v[22:25], v[220:223], v[14:17], v[22:25]
	s_waitcnt vmcnt(1)
	v_mfma_f32_16x16x32_bf16 v[26:29], v[224:227], v[14:17], v[26:29]
	s_waitcnt vmcnt(0)
	v_mfma_f32_16x16x32_bf16 v[30:33], v[248:251], v[14:17], v[30:33]
	s_nop 3
	ds_write2st64_b32 v59, v18, v19 offset1:1
	ds_write2st64_b32 v59, v20, v21 offset0:2 offset1:3
	ds_write2st64_b32 v59, v22, v23 offset0:4 offset1:5
	ds_write2st64_b32 v59, v24, v25 offset0:6 offset1:7
	s_nop 0
	ds_write2st64_b32 v59, v26, v27 offset0:8 offset1:9
	ds_write2st64_b32 v59, v28, v29 offset0:10 offset1:11
	s_nop 0
	ds_write2st64_b32 v59, v30, v31 offset0:12 offset1:13
	ds_write2st64_b32 v59, v32, v33 offset0:14 offset1:15
	s_waitcnt lgkmcnt(0)
	s_barrier
	s_and_saveexec_b64 s[6:7], s[4:5]
	s_cbranch_execz .LBB0_1469
	ds_read2st64_b32 v[18:19], v58 offset1:1
	ds_read2st64_b32 v[20:21], v58 offset0:16 offset1:17
	ds_read2st64_b32 v[22:23], v58 offset0:32 offset1:33
	ds_read2st64_b32 v[24:25], v58 offset0:48 offset1:49
	ds_read2st64_b32 v[26:27], v58 offset0:64 offset1:65
	ds_read2st64_b32 v[28:29], v58 offset0:80 offset1:81
	ds_read2st64_b32 v[30:31], v58 offset0:96 offset1:97
	ds_read2st64_b32 v[32:33], v58 offset0:112 offset1:113
	ds_read2st64_b32 v[40:41], v58 offset0:2 offset1:3
	ds_read2st64_b32 v[42:43], v58 offset0:18 offset1:19
	ds_read2st64_b32 v[44:45], v58 offset0:34 offset1:35
	ds_read2st64_b32 v[46:47], v58 offset0:50 offset1:51
	ds_read2st64_b32 v[48:49], v58 offset0:66 offset1:67
	ds_read2st64_b32 v[50:51], v58 offset0:82 offset1:83
	ds_read2st64_b32 v[52:53], v58 offset0:98 offset1:99
	ds_read2st64_b32 v[54:55], v58 offset0:114 offset1:115
	s_waitcnt lgkmcnt(7)
	v_pk_add_f32 v[40:41], v[40:41], 0 op_sel_hi:[1,0]
	v_pk_add_f32 v[18:19], v[18:19], 0 op_sel_hi:[1,0]
	s_ashr_i32 s9, s8, 31
	v_pk_add_f32 v[18:19], v[18:19], v[20:21]
	s_waitcnt lgkmcnt(6)
	v_pk_add_f32 v[20:21], v[40:41], v[42:43]
	v_pk_add_f32 v[18:19], v[18:19], v[22:23]
	s_waitcnt lgkmcnt(5)
	v_pk_add_f32 v[20:21], v[20:21], v[44:45]
	v_pk_add_f32 v[18:19], v[18:19], v[24:25]
	s_waitcnt lgkmcnt(4)
	v_pk_add_f32 v[20:21], v[20:21], v[46:47]
	v_pk_add_f32 v[18:19], v[18:19], v[26:27]
	s_waitcnt lgkmcnt(3)
	v_pk_add_f32 v[20:21], v[20:21], v[48:49]
	v_pk_add_f32 v[18:19], v[18:19], v[28:29]
	s_waitcnt lgkmcnt(2)
	v_pk_add_f32 v[20:21], v[20:21], v[50:51]
	v_pk_add_f32 v[18:19], v[18:19], v[30:31]
	s_waitcnt lgkmcnt(1)
	v_pk_add_f32 v[20:21], v[20:21], v[52:53]
	v_pk_add_f32 v[40:41], v[18:19], v[32:33]
	s_waitcnt lgkmcnt(0)
	v_pk_add_f32 v[42:43], v[20:21], v[54:55]
	ds_read2st64_b32 v[18:19], v58 offset0:4 offset1:5
	ds_read2st64_b32 v[20:21], v58 offset0:20 offset1:21
	ds_read2st64_b32 v[22:23], v58 offset0:36 offset1:37
	ds_read2st64_b32 v[24:25], v58 offset0:52 offset1:53
	ds_read2st64_b32 v[26:27], v58 offset0:68 offset1:69
	ds_read2st64_b32 v[28:29], v58 offset0:84 offset1:85
	ds_read2st64_b32 v[30:31], v58 offset0:100 offset1:101
	ds_read2st64_b32 v[32:33], v58 offset0:116 offset1:117
	ds_read2st64_b32 v[44:45], v58 offset0:6 offset1:7
	ds_read2st64_b32 v[46:47], v58 offset0:22 offset1:23
	ds_read2st64_b32 v[48:49], v58 offset0:38 offset1:39
	ds_read2st64_b32 v[50:51], v58 offset0:54 offset1:55
	ds_read2st64_b32 v[52:53], v58 offset0:70 offset1:71
	ds_read2st64_b32 v[54:55], v58 offset0:86 offset1:87
	ds_read2st64_b32 v[56:57], v58 offset0:102 offset1:103
	ds_read2st64_b32 v[60:61], v58 offset0:118 offset1:119
	s_waitcnt lgkmcnt(7)
; template <class Epi, class Pre>
; __device__ __forceinline__ void meta_gemm(const bf16_t* __restrict__ A, int lda, const bf16_t* __restrict__ Bt, int ldb, int N, int K, Epi& epi, Pre pre) {
;     ...
;           for (int j = 0; j < 4; ++j) { float s = 0.f;
; #pragma unroll
;             for (int w = 0; w < 8; ++w) s += part[(w * 16 + (bj * 2 + n) * 4 + j) * 64 + lane];
;             v[bj][n][j] = s; }
;       pre(fr, fq);
;       epi(NREAL + 16 * wid + fr, cb, fq, v[0][0], v[0][1], v[1][0], v[1][1]);
	v_pk_add_f32 v[44:45], v[44:45], 0 op_sel_hi:[1,0]
	v_pk_add_f32 v[18:19], v[18:19], 0 op_sel_hi:[1,0]
	s_lshl_b64 s[8:9], s[8:9], 2
	v_pk_add_f32 v[18:19], v[18:19], v[20:21]
	s_waitcnt lgkmcnt(6)
	v_pk_add_f32 v[20:21], v[44:45], v[46:47]
	v_pk_add_f32 v[18:19], v[18:19], v[22:23]
	s_waitcnt lgkmcnt(5)
	v_pk_add_f32 v[20:21], v[20:21], v[48:49]
	v_pk_add_f32 v[18:19], v[18:19], v[24:25]
	s_waitcnt lgkmcnt(4)
	v_pk_add_f32 v[20:21], v[20:21], v[50:51]
	v_pk_add_f32 v[18:19], v[18:19], v[26:27]
	s_waitcnt lgkmcnt(3)
	v_pk_add_f32 v[20:21], v[20:21], v[52:53]
	v_pk_add_f32 v[18:19], v[18:19], v[28:29]
	s_waitcnt lgkmcnt(2)
	v_pk_add_f32 v[20:21], v[20:21], v[54:55]
	v_pk_add_f32 v[18:19], v[18:19], v[30:31]
	s_waitcnt lgkmcnt(1)
	v_pk_add_f32 v[20:21], v[20:21], v[56:57]
	v_pk_add_f32 v[44:45], v[18:19], v[32:33]
	s_waitcnt lgkmcnt(0)
	v_pk_add_f32 v[46:47], v[20:21], v[60:61]
	ds_read2st64_b32 v[18:19], v58 offset0:8 offset1:9
	ds_read2st64_b32 v[20:21], v58 offset0:24 offset1:25
	ds_read2st64_b32 v[22:23], v58 offset0:40 offset1:41
	ds_read2st64_b32 v[24:25], v58 offset0:56 offset1:57
	ds_read2st64_b32 v[26:27], v58 offset0:72 offset1:73
	ds_read2st64_b32 v[28:29], v58 offset0:88 offset1:89
	ds_read2st64_b32 v[30:31], v58 offset0:104 offset1:105
	ds_read2st64_b32 v[32:33], v58 offset0:120 offset1:121
	ds_read2st64_b32 v[48:49], v58 offset0:10 offset1:11
	ds_read2st64_b32 v[50:51], v58 offset0:26 offset1:27
	ds_read2st64_b32 v[52:53], v58 offset0:42 offset1:43
	ds_read2st64_b32 v[54:55], v58 offset0:58 offset1:59
	ds_read2st64_b32 v[56:57], v58 offset0:74 offset1:75
	ds_read2st64_b32 v[60:61], v58 offset0:90 offset1:91
	ds_read2st64_b32 v[62:63], v58 offset0:106 offset1:107
	ds_read2st64_b32 v[64:65], v58 offset0:122 offset1:123
	s_waitcnt lgkmcnt(7)
	v_pk_add_f32 v[48:49], v[48:49], 0 op_sel_hi:[1,0]
	v_pk_add_f32 v[18:19], v[18:19], 0 op_sel_hi:[1,0]
	s_nop 0
	v_pk_add_f32 v[18:19], v[18:19], v[20:21]
	s_waitcnt lgkmcnt(6)
	v_pk_add_f32 v[20:21], v[48:49], v[50:51]
	v_pk_add_f32 v[18:19], v[18:19], v[22:23]
	s_waitcnt lgkmcnt(5)
	v_pk_add_f32 v[20:21], v[20:21], v[52:53]
	v_pk_add_f32 v[18:19], v[18:19], v[24:25]
	s_waitcnt lgkmcnt(4)
	v_pk_add_f32 v[20:21], v[20:21], v[54:55]
	v_pk_add_f32 v[18:19], v[18:19], v[26:27]
	s_waitcnt lgkmcnt(3)
	v_pk_add_f32 v[20:21], v[20:21], v[56:57]
	v_pk_add_f32 v[18:19], v[18:19], v[28:29]
	s_waitcnt lgkmcnt(2)
	v_pk_add_f32 v[20:21], v[20:21], v[60:61]
	v_pk_add_f32 v[18:19], v[18:19], v[30:31]
	s_waitcnt lgkmcnt(1)
	v_pk_add_f32 v[20:21], v[20:21], v[62:63]
	v_pk_add_f32 v[48:49], v[18:19], v[32:33]
	s_waitcnt lgkmcnt(0)
	v_pk_add_f32 v[50:51], v[20:21], v[64:65]
	ds_read2st64_b32 v[18:19], v58 offset0:12 offset1:13
	ds_read2st64_b32 v[20:21], v58 offset0:28 offset1:29
	ds_read2st64_b32 v[22:23], v58 offset0:44 offset1:45
	ds_read2st64_b32 v[24:25], v58 offset0:60 offset1:61
	ds_read2st64_b32 v[26:27], v58 offset0:76 offset1:77
	ds_read2st64_b32 v[28:29], v58 offset0:92 offset1:93
	ds_read2st64_b32 v[30:31], v58 offset0:108 offset1:109
	ds_read2st64_b32 v[32:33], v58 offset0:124 offset1:125
	ds_read2st64_b32 v[52:53], v58 offset0:14 offset1:15
	ds_read2st64_b32 v[54:55], v58 offset0:30 offset1:31
	ds_read2st64_b32 v[56:57], v58 offset0:46 offset1:47
	ds_read2st64_b32 v[60:61], v58 offset0:62 offset1:63
	ds_read2st64_b32 v[62:63], v58 offset0:78 offset1:79
	ds_read2st64_b32 v[64:65], v58 offset0:94 offset1:95
	ds_read2st64_b32 v[66:67], v58 offset0:110 offset1:111
	ds_read2st64_b32 v[68:69], v58 offset0:126 offset1:127
	s_waitcnt lgkmcnt(7)
	v_pk_add_f32 v[52:53], v[52:53], 0 op_sel_hi:[1,0]
	v_pk_add_f32 v[18:19], v[18:19], 0 op_sel_hi:[1,0]
	s_nop 0
	v_pk_add_f32 v[18:19], v[18:19], v[20:21]
	s_waitcnt lgkmcnt(6)
	v_pk_add_f32 v[20:21], v[52:53], v[54:55]
	v_pk_add_f32 v[18:19], v[18:19], v[22:23]
	s_waitcnt lgkmcnt(5)
	v_pk_add_f32 v[20:21], v[20:21], v[56:57]
	v_pk_add_f32 v[18:19], v[18:19], v[24:25]
	s_waitcnt lgkmcnt(4)
	v_pk_add_f32 v[20:21], v[20:21], v[60:61]
	v_pk_add_f32 v[18:19], v[18:19], v[26:27]
	s_waitcnt lgkmcnt(3)
	v_pk_add_f32 v[20:21], v[20:21], v[62:63]
	v_pk_add_f32 v[18:19], v[18:19], v[28:29]
	s_waitcnt lgkmcnt(2)
	v_pk_add_f32 v[20:21], v[20:21], v[64:65]
	v_pk_add_f32 v[18:19], v[18:19], v[30:31]
	s_waitcnt lgkmcnt(1)
	v_pk_add_f32 v[20:21], v[20:21], v[66:67]
	v_lshl_add_u64 v[30:31], v[38:39], 0, s[8:9]
	v_pk_add_f32 v[52:53], v[18:19], v[32:33]
	s_waitcnt lgkmcnt(0)
	v_pk_add_f32 v[54:55], v[20:21], v[68:69]
	global_load_dwordx4 v[18:21], v[30:31], off
	global_load_dwordx4 v[22:25], v[30:31], off offset:64
	global_load_dwordx4 v[26:29], v[30:31], off offset:512
	s_nop 0
	global_load_dwordx4 v[30:33], v[30:31], off offset:576
	v_lshl_add_u64 v[56:57], v[36:37], 0, s[8:9]
	s_waitcnt vmcnt(3)
	v_pk_add_f32 v[20:21], v[42:43], v[20:21]
	v_pk_add_f32 v[18:19], v[40:41], v[18:19]
	global_store_dwordx4 v[56:57], v[18:21], off
	s_waitcnt vmcnt(3)
	s_nop 0
	v_pk_add_f32 v[20:21], v[46:47], v[24:25]
	v_pk_add_f32 v[18:19], v[44:45], v[22:23]
	global_store_dwordx4 v[56:57], v[18:21], off offset:64
	s_waitcnt vmcnt(3)
	s_nop 0
	v_pk_add_f32 v[20:21], v[50:51], v[28:29]
	v_pk_add_f32 v[18:19], v[48:49], v[26:27]
	global_store_dwordx4 v[56:57], v[18:21], off offset:512
	s_waitcnt vmcnt(3)
	s_nop 0
	v_pk_add_f32 v[20:21], v[54:55], v[32:33]
	v_pk_add_f32 v[18:19], v[52:53], v[30:31]
	global_store_dwordx4 v[56:57], v[18:21], off offset:576
	s_branch .LBB0_1469

; template <class Epi, class Pre>
; __device__ __forceinline__ void meta_gemm(const bf16_t* __restrict__ A, int lda, const bf16_t* __restrict__ Bt, int ldb, int N, int K, Epi& epi, Pre pre) {
;     ...
;     const bf16_t* ap = A + (size_t)(NREAL + fr) * lda + wid * ks + fq * 8;
;     const bf16_t* bp = Bt + (size_t)(cb + fr) * ldb + wid * ks + fq * 8;
; #pragma unroll 4
;     for (int k0 = 0; k0 < ks; k0 += 32) {
;       const bf16x8 a = *(const bf16x8*)(ap + k0);
; #pragma unroll
;       for (int bj = 0; bj < 2; ++bj)
; #pragma unroll
;         for (int n = 0; n < 2; ++n) { const bf16x8 b = *(const bf16x8*)(bp + (size_t)(bj * 128 + n * 16) * ldb + k0); acc[bj][n] = __builtin_amdgcn_mfma_f32_16x16x32_bf16(b, a, acc[bj][n], 0, 0, 0); }
;     }
; #pragma unroll
;     for (int bj = 0; bj < 2; ++bj)
; #pragma unroll
;       for (int n = 0; n < 2; ++n)
; #pragma unroll
;         for (int j = 0; j < 4; ++j) part[(wid * 16 + (bj * 2 + n) * 4 + j) * 64 + lane] = acc[bj][n][j];
;     __syncthreads();
;     if (wid < 4) {
;       f32x4 v[2][2];
; #pragma unroll
;       for (int bj = 0; bj < 2; ++bj)
; #pragma unroll
;         for (int n = 0; n < 2; ++n)
; #pragma unroll
;           for (int j = 0; j < 4; ++j) { float s = 0.f;
; #pragma unroll
;             for (int w = 0; w < 8; ++w) s += part[(w * 16 + (bj * 2 + n) * 4 + j) * 64 + lane];
.LBB0_1515:
	s_and_b32 s6, s1, 0xffffff00
	s_and_b32 s12, s10, 0x60
	v_or_b32_e32 v23, s6, v0
	v_or_b32_e32 v24, s12, v23
	v_ashrrev_i32_e32 v25, 31, v24
	v_lshlrev_b64 v[24:25], 11, v[24:25]
	v_lshl_add_u64 v[44:45], v[18:19], 0, v[24:25]
	global_load_dwordx4 v[24:27], v[44:45], off
	global_load_dwordx4 v[40:43], v[44:45], off offset:64
	v_add_co_u32_e32 v46, vcc, 0x8000, v44
	v_addc_co_u32_e32 v47, vcc, 0, v45, vcc
	v_add_co_u32_e32 v48, vcc, 0x40000, v44
	v_addc_co_u32_e32 v49, vcc, 0, v45, vcc
	v_add_co_u32_e32 v50, vcc, 0x48000, v44
	v_addc_co_u32_e32 v51, vcc, 0, v45, vcc
	global_load_dwordx4 v[160:163], v[46:47], off
	global_load_dwordx4 v[168:171], v[46:47], off offset:64
	global_load_dwordx4 v[172:175], v[48:49], off
	global_load_dwordx4 v[176:179], v[48:49], off offset:64
	global_load_dwordx4 v[180:183], v[50:51], off
	global_load_dwordx4 v[184:187], v[50:51], off offset:64
	global_load_dwordx4 v[188:191], v[44:45], off offset:128
	global_load_dwordx4 v[192:195], v[46:47], off offset:128
	global_load_dwordx4 v[196:199], v[48:49], off offset:128
	global_load_dwordx4 v[200:203], v[50:51], off offset:128
	global_load_dwordx4 v[204:207], v[44:45], off offset:192
	global_load_dwordx4 v[220:223], v[46:47], off offset:192
	global_load_dwordx4 v[224:227], v[48:49], off offset:192
	global_load_dwordx4 v[248:251], v[50:51], off offset:192
	s_waitcnt vmcnt(15)
	v_mfma_f32_16x16x32_bf16 v[24:27], v[24:27], v[10:13], 0
	s_waitcnt vmcnt(14)
	v_mfma_f32_16x16x32_bf16 v[24:27], v[40:43], v[2:5], v[24:27]
	s_waitcnt vmcnt(13)
	v_mfma_f32_16x16x32_bf16 v[28:31], v[160:163], v[10:13], 0
	s_waitcnt vmcnt(12)
	v_mfma_f32_16x16x32_bf16 v[28:31], v[168:171], v[2:5], v[28:31]
	s_waitcnt vmcnt(11)
	v_mfma_f32_16x16x32_bf16 v[32:35], v[172:175], v[10:13], 0
	s_waitcnt vmcnt(10)
	v_mfma_f32_16x16x32_bf16 v[32:35], v[176:179], v[2:5], v[32:35]
	s_waitcnt vmcnt(9)
	v_mfma_f32_16x16x32_bf16 v[36:39], v[180:183], v[10:13], 0
	s_waitcnt vmcnt(8)
	v_mfma_f32_16x16x32_bf16 v[36:39], v[184:187], v[2:5], v[36:39]
	s_waitcnt vmcnt(7)
	v_mfma_f32_16x16x32_bf16 v[24:27], v[188:191], v[6:9], v[24:27]
	s_waitcnt vmcnt(6)
	v_mfma_f32_16x16x32_bf16 v[28:31], v[192:195], v[6:9], v[28:31]
	s_waitcnt vmcnt(5)
	v_mfma_f32_16x16x32_bf16 v[32:35], v[196:199], v[6:9], v[32:35]
	s_waitcnt vmcnt(4)
	v_mfma_f32_16x16x32_bf16 v[36:39], v[200:203], v[6:9], v[36:39]
	s_waitcnt vmcnt(3)
	v_mfma_f32_16x16x32_bf16 v[24:27], v[204:207], v[14:17], v[24:27]
	s_waitcnt vmcnt(2)
	v_mfma_f32_16x16x32_bf16 v[28:31], v[220:223], v[14:17], v[28:31]
	s_waitcnt vmcnt(1)
	v_mfma_f32_16x16x32_bf16 v[32:35], v[224:227], v[14:17], v[32:35]
	s_waitcnt vmcnt(0)
	v_mfma_f32_16x16x32_bf16 v[36:39], v[248:251], v[14:17], v[36:39]
	s_nop 3
	ds_write2st64_b32 v75, v24, v25 offset1:1
	ds_write2st64_b32 v75, v26, v27 offset0:2 offset1:3
	ds_write2st64_b32 v75, v28, v29 offset0:4 offset1:5
	ds_write2st64_b32 v75, v30, v31 offset0:6 offset1:7
	s_nop 0
	ds_write2st64_b32 v75, v32, v33 offset0:8 offset1:9
	ds_write2st64_b32 v75, v34, v35 offset0:10 offset1:11
	s_nop 0
	ds_write2st64_b32 v75, v36, v37 offset0:12 offset1:13
	ds_write2st64_b32 v75, v38, v39 offset0:14 offset1:15
	s_waitcnt lgkmcnt(0)
	s_barrier
	s_and_saveexec_b64 s[6:7], s[4:5]
	s_cbranch_execz .LBB0_1514
	ds_read2st64_b32 v[76:77], v74 offset1:1
	ds_read2st64_b32 v[38:39], v74 offset0:2 offset1:3
	ds_read2st64_b32 v[72:73], v74 offset0:4 offset1:5
	ds_read2st64_b32 v[24:25], v74 offset0:6 offset1:7
	ds_read2st64_b32 v[78:79], v74 offset0:16 offset1:17
	ds_read2st64_b32 v[42:43], v74 offset0:18 offset1:19
	ds_read2st64_b32 v[80:81], v74 offset0:20 offset1:21
	ds_read2st64_b32 v[26:27], v74 offset0:22 offset1:23
	ds_read2st64_b32 v[82:83], v74 offset0:32 offset1:33
	ds_read2st64_b32 v[44:45], v74 offset0:34 offset1:35
	ds_read2st64_b32 v[84:85], v74 offset0:36 offset1:37
	ds_read2st64_b32 v[28:29], v74 offset0:38 offset1:39
	ds_read2st64_b32 v[86:87], v74 offset0:48 offset1:49
	ds_read2st64_b32 v[46:47], v74 offset0:50 offset1:51
	ds_read2st64_b32 v[88:89], v74 offset0:52 offset1:53
	ds_read2st64_b32 v[30:31], v74 offset0:54 offset1:55
	ds_read2st64_b32 v[90:91], v74 offset0:64 offset1:65
	ds_read2st64_b32 v[48:49], v74 offset0:66 offset1:67
	ds_read2st64_b32 v[92:93], v74 offset0:68 offset1:69
	ds_read2st64_b32 v[32:33], v74 offset0:70 offset1:71
	ds_read2st64_b32 v[94:95], v74 offset0:80 offset1:81
	ds_read2st64_b32 v[50:51], v74 offset0:82 offset1:83
	ds_read2st64_b32 v[96:97], v74 offset0:84 offset1:85
	ds_read2st64_b32 v[34:35], v74 offset0:86 offset1:87
	ds_read2st64_b32 v[98:99], v74 offset0:96 offset1:97
	ds_read2st64_b32 v[52:53], v74 offset0:98 offset1:99
	ds_read2st64_b32 v[100:101], v74 offset0:100 offset1:101
	ds_read2st64_b32 v[36:37], v74 offset0:102 offset1:103
	ds_read2st64_b32 v[102:103], v74 offset0:112 offset1:113
	ds_read2st64_b32 v[54:55], v74 offset0:114 offset1:115
	ds_read2st64_b32 v[104:105], v74 offset0:116 offset1:117
	ds_read2st64_b32 v[40:41], v74 offset0:118 offset1:119
	ds_read2st64_b32 v[106:107], v74 offset0:8 offset1:9
	ds_read2st64_b32 v[108:109], v74 offset0:10 offset1:11
	ds_read2st64_b32 v[110:111], v74 offset0:12 offset1:13
	ds_read2st64_b32 v[60:61], v74 offset0:14 offset1:15
	ds_read2st64_b32 v[112:113], v74 offset0:24 offset1:25
	ds_read2st64_b32 v[114:115], v74 offset0:26 offset1:27
	ds_read2st64_b32 v[116:117], v74 offset0:28 offset1:29
	ds_read2st64_b32 v[64:65], v74 offset0:30 offset1:31
	ds_read2st64_b32 v[118:119], v74 offset0:40 offset1:41
	ds_read2st64_b32 v[120:121], v74 offset0:42 offset1:43
	ds_read2st64_b32 v[122:123], v74 offset0:44 offset1:45
	ds_read2st64_b32 v[66:67], v74 offset0:46 offset1:47
	ds_read2st64_b32 v[124:125], v74 offset0:56 offset1:57
	ds_read2st64_b32 v[126:127], v74 offset0:58 offset1:59
	ds_read2st64_b32 v[128:129], v74 offset0:60 offset1:61
	ds_read2st64_b32 v[70:71], v74 offset0:62 offset1:63
	ds_read2st64_b32 v[130:131], v74 offset0:72 offset1:73
	ds_read2st64_b32 v[132:133], v74 offset0:74 offset1:75
	ds_read2st64_b32 v[134:135], v74 offset0:76 offset1:77
	ds_read2st64_b32 v[56:57], v74 offset0:78 offset1:79
	ds_read2st64_b32 v[136:137], v74 offset0:88 offset1:89
	ds_read2st64_b32 v[138:139], v74 offset0:90 offset1:91
	ds_read2st64_b32 v[140:141], v74 offset0:92 offset1:93
	ds_read2st64_b32 v[58:59], v74 offset0:94 offset1:95
	ds_read2st64_b32 v[142:143], v74 offset0:104 offset1:105
	ds_read2st64_b32 v[144:145], v74 offset0:106 offset1:107
	ds_read2st64_b32 v[146:147], v74 offset0:108 offset1:109
	ds_read2st64_b32 v[62:63], v74 offset0:110 offset1:111
	ds_read2st64_b32 v[148:149], v74 offset0:120 offset1:121
	ds_read2st64_b32 v[150:151], v74 offset0:122 offset1:123
	ds_read2st64_b32 v[152:153], v74 offset0:124 offset1:125
	ds_read2st64_b32 v[68:69], v74 offset0:126 offset1:127
	s_waitcnt lgkmcnt(14)
; __device__ __forceinline__ unsigned cvt_pk_bf16(float lo, float hi) { const f32x2 v = {lo, hi}; return __builtin_bit_cast(unsigned, __builtin_convertvector(v, bf16v2)); }
;   __device__ __forceinline__ void operator()(int row, int cb, int fq, f32x4 a, f32x4 b, f32x4 c, f32x4 d) const { group(row, cb, fq, a, b); group(row, cb + 128, fq, c, d); }
;   __device__ __forceinline__ void operator()(int row, int cb, int fq, f32x4 a, f32x4 b, f32x4 c, f32x4 d) const { group(row, cb, fq, a, b); group(row, cb + 128, fq, c, d); }
; __device__ __forceinline__ float silu_mul(float g, float u) { return g * __builtin_amdgcn_rcpf(1.0f + __builtin_amdgcn_exp2f(-g * LOG2E)) * u; }
;   __device__ __forceinline__ void operator()(int row, int cb, int fq, f32x4 g0, f32x4 g1, f32x4 u0, f32x4 u1) const {
;     bf16_t* p = act + (size_t)row * DFF + (cb >> 8) * 128 + (cb & 255) + fq * 8; f32x4 o0, o1;
; #pragma unroll
;     for (int j = 0; j < 4; ++j) { o0[j] = silu_mul(g0[j], u0[j]); o1[j] = silu_mul(g1[j], u1[j]); }
;     u32x4 w; w.x = cvt_pk_bf16(o0[0], o0[1]); w.y = cvt_pk_bf16(o0[2], o0[3]); w.z = cvt_pk_bf16(o1[0], o1[1]); w.w = cvt_pk_bf16(o1[2], o1[3]);
;     *(u32x4*)p = w;
; template <class Epi, class Pre>
; __device__ __forceinline__ void meta_gemm(const bf16_t* __restrict__ A, int lda, const bf16_t* __restrict__ Bt, int ldb, int N, int K, Epi& epi, Pre pre) {
;     ...
; #pragma unroll
;       for (int bj = 0; bj < 2; ++bj)
; #pragma unroll
;         for (int n = 0; n < 2; ++n)
; #pragma unroll
;           for (int j = 0; j < 4; ++j) { float s = 0.f;
; #pragma unroll
;             for (int w = 0; w < 8; ++w) s += part[(w * 16 + (bj * 2 + n) * 4 + j) * 64 + lane];
;             v[bj][n][j] = s; }
;       pre(fr, fq);
;       epi(NREAL + 16 * wid + fr, cb, fq, v[0][0], v[0][1], v[1][0], v[1][1]);
	v_pk_add_f32 v[76:77], v[76:77], 0 op_sel_hi:[1,0]
	v_pk_add_f32 v[72:73], v[72:73], 0 op_sel_hi:[1,0]
	v_pk_add_f32 v[76:77], v[76:77], v[78:79]
	v_pk_add_f32 v[72:73], v[72:73], v[80:81]
	v_pk_add_f32 v[76:77], v[76:77], v[82:83]
	v_pk_add_f32 v[72:73], v[72:73], v[84:85]
	v_pk_add_f32 v[76:77], v[76:77], v[86:87]
	v_pk_add_f32 v[72:73], v[72:73], v[88:89]
	v_pk_add_f32 v[76:77], v[76:77], v[90:91]
	v_pk_add_f32 v[72:73], v[72:73], v[92:93]
	v_pk_add_f32 v[76:77], v[76:77], v[94:95]
	v_pk_add_f32 v[72:73], v[72:73], v[96:97]
	v_pk_add_f32 v[76:77], v[76:77], v[98:99]
	v_pk_add_f32 v[72:73], v[72:73], v[100:101]
	v_pk_add_f32 v[76:77], v[76:77], v[102:103]
	v_pk_add_f32 v[72:73], v[72:73], v[104:105]
	v_mul_f32_e32 v23, 0xbfb8aa3b, v76
	v_exp_f32_e32 v23, v23
	v_mul_f32_e32 v82, 0xbfb8aa3b, v77
	v_exp_f32_e32 v83, v82
	v_pk_add_f32 v[38:39], v[38:39], 0 op_sel_hi:[1,0]
	v_add_f32_e32 v23, 1.0, v23
	v_rcp_f32_e32 v82, v23
	v_add_f32_e32 v23, 1.0, v83
	v_rcp_f32_e32 v83, v23
	v_mul_f32_e32 v23, 0xbfb8aa3b, v72
	v_pk_add_f32 v[38:39], v[38:39], v[42:43]
	v_exp_f32_e32 v23, v23
	v_mul_f32_e32 v80, 0xbfb8aa3b, v73
	v_pk_add_f32 v[38:39], v[38:39], v[44:45]
	v_exp_f32_e32 v81, v80
	v_pk_add_f32 v[38:39], v[38:39], v[46:47]
	v_add_f32_e32 v23, 1.0, v23
	v_pk_add_f32 v[38:39], v[38:39], v[48:49]
	v_rcp_f32_e32 v80, v23
	v_pk_add_f32 v[38:39], v[38:39], v[50:51]
	v_add_f32_e32 v23, 1.0, v81
	v_pk_add_f32 v[38:39], v[38:39], v[52:53]
	v_pk_add_f32 v[24:25], v[24:25], 0 op_sel_hi:[1,0]
	v_pk_add_f32 v[38:39], v[38:39], v[54:55]
	v_rcp_f32_e32 v81, v23
	v_mul_f32_e32 v23, 0xbfb8aa3b, v38
	v_pk_add_f32 v[24:25], v[24:25], v[26:27]
	v_exp_f32_e32 v23, v23
	v_mul_f32_e32 v44, 0xbfb8aa3b, v39
	v_pk_add_f32 v[24:25], v[24:25], v[28:29]
	v_exp_f32_e32 v45, v44
	v_pk_add_f32 v[24:25], v[24:25], v[30:31]
	v_pk_add_f32 v[78:79], v[106:107], 0 op_sel_hi:[1,0]
	v_pk_add_f32 v[24:25], v[24:25], v[32:33]
	v_pk_add_f32 v[78:79], v[78:79], v[112:113]
	v_pk_add_f32 v[24:25], v[24:25], v[34:35]
	v_add_f32_e32 v23, 1.0, v23
	v_pk_add_f32 v[24:25], v[24:25], v[36:37]
	v_pk_add_f32 v[78:79], v[78:79], v[118:119]
	v_rcp_f32_e32 v44, v23
	v_add_f32_e32 v23, 1.0, v45
	v_pk_add_f32 v[24:25], v[24:25], v[40:41]
	v_pk_add_f32 v[78:79], v[78:79], v[124:125]
	v_rcp_f32_e32 v45, v23
	v_mul_f32_e32 v23, 0xbfb8aa3b, v24
	v_pk_add_f32 v[78:79], v[78:79], v[130:131]
	v_exp_f32_e32 v23, v23
	v_mul_f32_e32 v28, 0xbfb8aa3b, v25
	s_waitcnt lgkmcnt(11)
	v_pk_add_f32 v[78:79], v[78:79], v[136:137]
	v_exp_f32_e32 v29, v28
	s_waitcnt lgkmcnt(7)
	v_pk_add_f32 v[78:79], v[78:79], v[142:143]
	v_pk_mul_f32 v[76:77], v[76:77], v[82:83]
	s_waitcnt lgkmcnt(3)
	v_pk_add_f32 v[78:79], v[78:79], v[148:149]
	v_pk_add_f32 v[26:27], v[60:61], 0 op_sel_hi:[1,0]
	v_pk_mul_f32 v[76:77], v[76:77], v[78:79]
	v_pk_add_f32 v[78:79], v[110:111], 0 op_sel_hi:[1,0]
	v_pk_add_f32 v[42:43], v[108:109], 0 op_sel_hi:[1,0]
	v_pk_add_f32 v[26:27], v[26:27], v[64:65]
	v_add_f32_e32 v23, 1.0, v23
	v_pk_add_f32 v[78:79], v[78:79], v[116:117]
	v_pk_add_f32 v[42:43], v[42:43], v[114:115]
	v_pk_add_f32 v[26:27], v[26:27], v[66:67]
	v_rcp_f32_e32 v28, v23
	v_add_f32_e32 v23, 1.0, v29
	v_pk_add_f32 v[78:79], v[78:79], v[122:123]
	v_pk_add_f32 v[42:43], v[42:43], v[120:121]
	v_pk_add_f32 v[26:27], v[26:27], v[70:71]
	v_rcp_f32_e32 v29, v23
	v_pk_add_f32 v[78:79], v[78:79], v[128:129]
	v_pk_add_f32 v[42:43], v[42:43], v[126:127]
	v_pk_add_f32 v[26:27], v[26:27], v[56:57]
	v_pk_add_f32 v[78:79], v[78:79], v[134:135]
	v_pk_add_f32 v[42:43], v[42:43], v[132:133]
	v_pk_add_f32 v[26:27], v[26:27], v[58:59]
	v_pk_add_f32 v[78:79], v[78:79], v[140:141]
	v_pk_add_f32 v[42:43], v[42:43], v[138:139]
	v_pk_add_f32 v[26:27], v[26:27], v[62:63]
	s_and_b32 s14, s10, 0xffffff80
	v_pk_add_f32 v[78:79], v[78:79], v[146:147]
	v_pk_add_f32 v[42:43], v[42:43], v[144:145]
	s_waitcnt lgkmcnt(0)
	v_pk_add_f32 v[26:27], v[26:27], v[68:69]
	v_pk_mul_f32 v[24:25], v[24:25], v[28:29]
	s_ashr_i32 s15, s14, 31
	v_pk_add_f32 v[78:79], v[78:79], v[152:153]
	v_pk_mul_f32 v[72:73], v[72:73], v[80:81]
	v_pk_add_f32 v[42:43], v[42:43], v[150:151]
	v_pk_mul_f32 v[38:39], v[38:39], v[44:45]
	v_pk_mul_f32 v[28:29], v[24:25], v[26:27]
	v_lshl_add_u64 v[24:25], s[14:15], 1, v[20:21]
	s_lshl_b32 s90, s12, 1
	v_pk_mul_f32 v[72:73], v[72:73], v[78:79]
	v_pk_mul_f32 v[38:39], v[38:39], v[42:43]
	v_lshl_add_u64 v[24:25], v[24:25], 0, s[90:91]
	v_mov_b32_e32 v23, v1
	v_lshl_add_u64 v[30:31], v[24:25], 0, v[22:23]
	v_cvt_pk_bf16_f32 v24, v76, v77
	v_cvt_pk_bf16_f32 v25, v38, v39
	v_cvt_pk_bf16_f32 v26, v72, v73
	v_cvt_pk_bf16_f32 v27, v28, v29
	global_store_dwordx4 v[30:31], v[24:27], off
	s_branch .LBB0_1514

; template <class Epi, class Pre>
; __device__ __forceinline__ void meta_gemm(const bf16_t* __restrict__ A, int lda, const bf16_t* __restrict__ Bt, int ldb, int N, int K, Epi& epi, Pre pre) {
;     ...
;     const bf16_t* ap = A + (size_t)(NREAL + fr) * lda + wid * ks + fq * 8;
;     const bf16_t* bp = Bt + (size_t)(cb + fr) * ldb + wid * ks + fq * 8;
; #pragma unroll 4
;     for (int k0 = 0; k0 < ks; k0 += 32) {
;       const bf16x8 a = *(const bf16x8*)(ap + k0);
; #pragma unroll
;       for (int bj = 0; bj < 2; ++bj)
; #pragma unroll
;         for (int n = 0; n < 2; ++n) { const bf16x8 b = *(const bf16x8*)(bp + (size_t)(bj * 128 + n * 16) * ldb + k0); acc[bj][n] = __builtin_amdgcn_mfma_f32_16x16x32_bf16(b, a, acc[bj][n], 0, 0, 0); }
;     }
.LBB0_1547:
	s_and_b32 s4, s10, 0x60
	s_and_b32 s5, s1, 0xffffff00
	s_or_b32 s4, s5, s4
	v_or_b32_e32 v2, s4, v0
	s_movk_i32 s5, 0x1600
	v_mad_i64_i32 v[34:35], s[8:9], v2, s5, v[24:25]
	v_add_co_u32_e32 v32, vcc, 0x16000, v34
	s_mov_b32 s5, 0xb0000
	s_nop 0
	v_addc_co_u32_e32 v33, vcc, 0, v35, vcc
	v_add_co_u32_e32 v30, vcc, s5, v34
	global_load_dwordx4 v[2:5], v[22:23], off
	global_load_dwordx4 v[6:9], v[34:35], off
	v_addc_co_u32_e32 v31, vcc, 0, v35, vcc
	v_add_co_u32_e32 v28, vcc, 0xc6000, v34
	global_load_dwordx4 v[10:13], v[32:33], off
	s_nop 0
	v_addc_co_u32_e32 v29, vcc, 0, v35, vcc
	global_load_dwordx4 v[14:17], v[30:31], off
	global_load_dwordx4 v[18:21], v[28:29], off
	global_load_dwordx4 v[54:57], v[22:23], off offset:64
	global_load_dwordx4 v[58:61], v[34:35], off offset:64
	global_load_dwordx4 v[62:65], v[32:33], off offset:64
	global_load_dwordx4 v[66:69], v[30:31], off offset:64
	global_load_dwordx4 v[70:73], v[28:29], off offset:64
	global_load_dwordx4 v[74:77], v[22:23], off offset:128
	global_load_dwordx4 v[78:81], v[34:35], off offset:128
	global_load_dwordx4 v[82:85], v[32:33], off offset:128
	global_load_dwordx4 v[86:89], v[30:31], off offset:128
	global_load_dwordx4 v[90:93], v[28:29], off offset:128
	global_load_dwordx4 v[94:97], v[22:23], off offset:192
	global_load_dwordx4 v[98:101], v[34:35], off offset:192
	global_load_dwordx4 v[102:105], v[32:33], off offset:192
	global_load_dwordx4 v[106:109], v[30:31], off offset:192
	global_load_dwordx4 v[110:113], v[28:29], off offset:192
	global_load_dwordx4 v[114:117], v[22:23], off offset:256
	global_load_dwordx4 v[118:121], v[34:35], off offset:256
	global_load_dwordx4 v[122:125], v[32:33], off offset:256
	global_load_dwordx4 v[126:129], v[30:31], off offset:256
	global_load_dwordx4 v[130:133], v[28:29], off offset:256
	global_load_dwordx4 v[134:137], v[22:23], off offset:320
	global_load_dwordx4 v[138:141], v[34:35], off offset:320
	global_load_dwordx4 v[142:145], v[32:33], off offset:320
	global_load_dwordx4 v[146:149], v[30:31], off offset:320
	global_load_dwordx4 v[150:153], v[28:29], off offset:320
	global_load_dwordx4 v[160:163], v[22:23], off offset:384
	global_load_dwordx4 v[168:171], v[34:35], off offset:384
	global_load_dwordx4 v[172:175], v[32:33], off offset:384
	global_load_dwordx4 v[176:179], v[30:31], off offset:384
	global_load_dwordx4 v[180:183], v[28:29], off offset:384
	s_waitcnt vmcnt(33)
	v_mfma_f32_16x16x32_bf16 v[6:9], v[6:9], v[2:5], 0
	s_waitcnt vmcnt(32)
	v_mfma_f32_16x16x32_bf16 v[10:13], v[10:13], v[2:5], 0
	s_waitcnt vmcnt(31)
	v_mfma_f32_16x16x32_bf16 v[14:17], v[14:17], v[2:5], 0
	s_waitcnt vmcnt(30)
	v_mfma_f32_16x16x32_bf16 v[2:5], v[18:21], v[2:5], 0
	s_waitcnt vmcnt(28)
	v_mfma_f32_16x16x32_bf16 v[6:9], v[58:61], v[54:57], v[6:9]
	s_waitcnt vmcnt(27)
	v_mfma_f32_16x16x32_bf16 v[10:13], v[62:65], v[54:57], v[10:13]
	s_waitcnt vmcnt(26)
	v_mfma_f32_16x16x32_bf16 v[14:17], v[66:69], v[54:57], v[14:17]
	s_waitcnt vmcnt(25)
	v_mfma_f32_16x16x32_bf16 v[2:5], v[70:73], v[54:57], v[2:5]
	s_waitcnt vmcnt(23)
	v_mfma_f32_16x16x32_bf16 v[6:9], v[78:81], v[74:77], v[6:9]
	s_waitcnt vmcnt(22)
	v_mfma_f32_16x16x32_bf16 v[10:13], v[82:85], v[74:77], v[10:13]
	s_waitcnt vmcnt(21)
	v_mfma_f32_16x16x32_bf16 v[14:17], v[86:89], v[74:77], v[14:17]
	s_waitcnt vmcnt(20)
	v_mfma_f32_16x16x32_bf16 v[2:5], v[90:93], v[74:77], v[2:5]
	s_waitcnt vmcnt(18)
	v_mfma_f32_16x16x32_bf16 v[6:9], v[98:101], v[94:97], v[6:9]
	s_waitcnt vmcnt(17)
	v_mfma_f32_16x16x32_bf16 v[10:13], v[102:105], v[94:97], v[10:13]
	s_waitcnt vmcnt(16)
	v_mfma_f32_16x16x32_bf16 v[14:17], v[106:109], v[94:97], v[14:17]
	s_waitcnt vmcnt(15)
	v_mfma_f32_16x16x32_bf16 v[2:5], v[110:113], v[94:97], v[2:5]
	s_nop 1
	global_load_dwordx4 v[54:57], v[22:23], off offset:448
	global_load_dwordx4 v[58:61], v[34:35], off offset:448
	global_load_dwordx4 v[62:65], v[32:33], off offset:448
	global_load_dwordx4 v[66:69], v[30:31], off offset:448
	global_load_dwordx4 v[70:73], v[28:29], off offset:448
	global_load_dwordx4 v[74:77], v[22:23], off offset:512
	global_load_dwordx4 v[78:81], v[34:35], off offset:512
	global_load_dwordx4 v[82:85], v[32:33], off offset:512
	global_load_dwordx4 v[86:89], v[30:31], off offset:512
	global_load_dwordx4 v[90:93], v[28:29], off offset:512
	global_load_dwordx4 v[94:97], v[22:23], off offset:576
	global_load_dwordx4 v[98:101], v[34:35], off offset:576
	global_load_dwordx4 v[102:105], v[32:33], off offset:576
	global_load_dwordx4 v[106:109], v[30:31], off offset:576
	global_load_dwordx4 v[110:113], v[28:29], off offset:576
	s_waitcnt vmcnt(28)
	v_mfma_f32_16x16x32_bf16 v[6:9], v[118:121], v[114:117], v[6:9]
	s_waitcnt vmcnt(27)
	v_mfma_f32_16x16x32_bf16 v[10:13], v[122:125], v[114:117], v[10:13]
	s_waitcnt vmcnt(26)
	v_mfma_f32_16x16x32_bf16 v[14:17], v[126:129], v[114:117], v[14:17]
	s_waitcnt vmcnt(25)
	v_mfma_f32_16x16x32_bf16 v[2:5], v[130:133], v[114:117], v[2:5]
	s_waitcnt vmcnt(23)
	v_mfma_f32_16x16x32_bf16 v[6:9], v[138:141], v[134:137], v[6:9]
	s_waitcnt vmcnt(22)
	v_mfma_f32_16x16x32_bf16 v[10:13], v[142:145], v[134:137], v[10:13]
	s_waitcnt vmcnt(21)
	v_mfma_f32_16x16x32_bf16 v[14:17], v[146:149], v[134:137], v[14:17]
	s_waitcnt vmcnt(20)
	v_mfma_f32_16x16x32_bf16 v[2:5], v[150:153], v[134:137], v[2:5]
	s_waitcnt vmcnt(18)
	v_mfma_f32_16x16x32_bf16 v[6:9], v[168:171], v[160:163], v[6:9]
	s_waitcnt vmcnt(17)
	v_mfma_f32_16x16x32_bf16 v[10:13], v[172:175], v[160:163], v[10:13]
	s_waitcnt vmcnt(16)
	v_mfma_f32_16x16x32_bf16 v[14:17], v[176:179], v[160:163], v[14:17]
	s_waitcnt vmcnt(15)
; template <class Epi, class Pre>
; __device__ __forceinline__ void meta_gemm(const bf16_t* __restrict__ A, int lda, const bf16_t* __restrict__ Bt, int ldb, int N, int K, Epi& epi, Pre pre) {
;     ...
;     }
; #pragma unroll
;     for (int bj = 0; bj < 2; ++bj)
; #pragma unroll
;       for (int n = 0; n < 2; ++n)
; #pragma unroll
;         for (int j = 0; j < 4; ++j) part[(wid * 16 + (bj * 2 + n) * 4 + j) * 64 + lane] = acc[bj][n][j];
;     __syncthreads();
;     if (wid < 4) {
;       f32x4 v[2][2];
; #pragma unroll
;       for (int bj = 0; bj < 2; ++bj)
; #pragma unroll
;         for (int n = 0; n < 2; ++n)
; #pragma unroll
;           for (int j = 0; j < 4; ++j) { float s = 0.f;
; #pragma unroll
;             for (int w = 0; w < 8; ++w) s += part[(w * 16 + (bj * 2 + n) * 4 + j) * 64 + lane];
	v_mfma_f32_16x16x32_bf16 v[2:5], v[180:183], v[160:163], v[2:5]
	s_nop 1
	global_load_dwordx4 v[114:117], v[22:23], off offset:640
	global_load_dwordx4 v[118:121], v[34:35], off offset:640
	global_load_dwordx4 v[122:125], v[32:33], off offset:640
	global_load_dwordx4 v[126:129], v[30:31], off offset:640
	global_load_dwordx4 v[130:133], v[28:29], off offset:640
	s_waitcnt vmcnt(18)
	v_mfma_f32_16x16x32_bf16 v[6:9], v[58:61], v[54:57], v[6:9]
	s_waitcnt vmcnt(17)
	v_mfma_f32_16x16x32_bf16 v[10:13], v[62:65], v[54:57], v[10:13]
	s_waitcnt vmcnt(16)
	v_mfma_f32_16x16x32_bf16 v[14:17], v[66:69], v[54:57], v[14:17]
	s_waitcnt vmcnt(15)
	v_mfma_f32_16x16x32_bf16 v[2:5], v[70:73], v[54:57], v[2:5]
	s_waitcnt vmcnt(13)
	v_mfma_f32_16x16x32_bf16 v[6:9], v[78:81], v[74:77], v[6:9]
	s_waitcnt vmcnt(12)
	v_mfma_f32_16x16x32_bf16 v[36:39], v[82:85], v[74:77], v[10:13]
	s_waitcnt vmcnt(11)
	v_mfma_f32_16x16x32_bf16 v[44:47], v[86:89], v[74:77], v[14:17]
	s_waitcnt vmcnt(10)
	v_mfma_f32_16x16x32_bf16 v[2:5], v[90:93], v[74:77], v[2:5]
	s_waitcnt vmcnt(8)
	v_mfma_f32_16x16x32_bf16 v[10:13], v[98:101], v[94:97], v[6:9]
	s_waitcnt vmcnt(7)
	v_mfma_f32_16x16x32_bf16 v[14:17], v[102:105], v[94:97], v[36:39]
	s_waitcnt vmcnt(6)
	v_mfma_f32_16x16x32_bf16 v[6:9], v[106:109], v[94:97], v[44:47]
	s_waitcnt vmcnt(5)
	v_mfma_f32_16x16x32_bf16 v[2:5], v[110:113], v[94:97], v[2:5]
	s_waitcnt vmcnt(3)
	v_mfma_f32_16x16x32_bf16 v[10:13], v[118:121], v[114:117], v[10:13]
	s_waitcnt vmcnt(2)
	v_mfma_f32_16x16x32_bf16 v[14:17], v[122:125], v[114:117], v[14:17]
	s_waitcnt vmcnt(1)
	v_mfma_f32_16x16x32_bf16 v[6:9], v[126:129], v[114:117], v[6:9]
	s_waitcnt vmcnt(0)
	v_mfma_f32_16x16x32_bf16 v[2:5], v[130:133], v[114:117], v[2:5]
	s_nop 3
	ds_write2st64_b32 v43, v10, v11 offset1:1
	ds_write2st64_b32 v43, v12, v13 offset0:2 offset1:3
	ds_write2st64_b32 v43, v14, v15 offset0:4 offset1:5
	ds_write2st64_b32 v43, v16, v17 offset0:6 offset1:7
	s_nop 0
	ds_write2st64_b32 v43, v6, v7 offset0:8 offset1:9
	ds_write2st64_b32 v43, v8, v9 offset0:10 offset1:11
	s_nop 0
	ds_write2st64_b32 v43, v2, v3 offset0:12 offset1:13
	ds_write2st64_b32 v43, v4, v5 offset0:14 offset1:15
	s_waitcnt lgkmcnt(0)
	s_barrier
	s_and_saveexec_b64 s[8:9], s[2:3]
	s_cbranch_execz .LBB0_1546
	ds_read2st64_b32 v[2:3], v42 offset1:1
	ds_read2st64_b32 v[4:5], v42 offset0:16 offset1:17
	ds_read2st64_b32 v[6:7], v42 offset0:32 offset1:33
	ds_read2st64_b32 v[8:9], v42 offset0:48 offset1:49
	ds_read2st64_b32 v[10:11], v42 offset0:64 offset1:65
	ds_read2st64_b32 v[12:13], v42 offset0:80 offset1:81
	ds_read2st64_b32 v[14:15], v42 offset0:96 offset1:97
	ds_read2st64_b32 v[16:17], v42 offset0:112 offset1:113
	ds_read2st64_b32 v[18:19], v42 offset0:2 offset1:3
	ds_read2st64_b32 v[20:21], v42 offset0:18 offset1:19
	ds_read2st64_b32 v[28:29], v42 offset0:34 offset1:35
	ds_read2st64_b32 v[30:31], v42 offset0:50 offset1:51
	ds_read2st64_b32 v[32:33], v42 offset0:66 offset1:67
	ds_read2st64_b32 v[34:35], v42 offset0:82 offset1:83
	ds_read2st64_b32 v[36:37], v42 offset0:98 offset1:99
	ds_read2st64_b32 v[38:39], v42 offset0:114 offset1:115
	s_waitcnt lgkmcnt(7)
	v_pk_add_f32 v[18:19], v[18:19], 0 op_sel_hi:[1,0]
	v_pk_add_f32 v[2:3], v[2:3], 0 op_sel_hi:[1,0]
	s_ashr_i32 s5, s4, 31
	v_pk_add_f32 v[2:3], v[2:3], v[4:5]
	s_waitcnt lgkmcnt(6)
	v_pk_add_f32 v[4:5], v[18:19], v[20:21]
	v_pk_add_f32 v[2:3], v[2:3], v[6:7]
	s_waitcnt lgkmcnt(5)
	v_pk_add_f32 v[4:5], v[4:5], v[28:29]
	v_pk_add_f32 v[2:3], v[2:3], v[8:9]
	s_waitcnt lgkmcnt(4)
	v_pk_add_f32 v[4:5], v[4:5], v[30:31]
	v_pk_add_f32 v[2:3], v[2:3], v[10:11]
	s_waitcnt lgkmcnt(3)
	v_pk_add_f32 v[4:5], v[4:5], v[32:33]
	v_pk_add_f32 v[2:3], v[2:3], v[12:13]
	s_waitcnt lgkmcnt(2)
	v_pk_add_f32 v[4:5], v[4:5], v[34:35]
	v_pk_add_f32 v[2:3], v[2:3], v[14:15]
	s_waitcnt lgkmcnt(1)
	v_pk_add_f32 v[4:5], v[4:5], v[36:37]
	v_pk_add_f32 v[18:19], v[2:3], v[16:17]
	s_waitcnt lgkmcnt(0)
	v_pk_add_f32 v[20:21], v[4:5], v[38:39]
	ds_read2st64_b32 v[2:3], v42 offset0:4 offset1:5
	ds_read2st64_b32 v[4:5], v42 offset0:20 offset1:21
	ds_read2st64_b32 v[6:7], v42 offset0:36 offset1:37
	ds_read2st64_b32 v[8:9], v42 offset0:52 offset1:53
	ds_read2st64_b32 v[10:11], v42 offset0:68 offset1:69
	ds_read2st64_b32 v[12:13], v42 offset0:84 offset1:85
	ds_read2st64_b32 v[14:15], v42 offset0:100 offset1:101
	ds_read2st64_b32 v[16:17], v42 offset0:116 offset1:117
	ds_read2st64_b32 v[28:29], v42 offset0:6 offset1:7
	ds_read2st64_b32 v[30:31], v42 offset0:22 offset1:23
	ds_read2st64_b32 v[32:33], v42 offset0:38 offset1:39
	ds_read2st64_b32 v[34:35], v42 offset0:54 offset1:55
	ds_read2st64_b32 v[36:37], v42 offset0:70 offset1:71
	ds_read2st64_b32 v[38:39], v42 offset0:86 offset1:87
	ds_read2st64_b32 v[40:41], v42 offset0:102 offset1:103
	ds_read2st64_b32 v[44:45], v42 offset0:118 offset1:119
	s_waitcnt lgkmcnt(7)
	v_pk_add_f32 v[28:29], v[28:29], 0 op_sel_hi:[1,0]
	v_pk_add_f32 v[2:3], v[2:3], 0 op_sel_hi:[1,0]
	s_nop 0
	v_pk_add_f32 v[2:3], v[2:3], v[4:5]
	s_waitcnt lgkmcnt(6)
; template <class Epi, class Pre>
; __device__ __forceinline__ void meta_gemm(const bf16_t* __restrict__ A, int lda, const bf16_t* __restrict__ Bt, int ldb, int N, int K, Epi& epi, Pre pre) {
;     ...
;           for (int j = 0; j < 4; ++j) { float s = 0.f;
; #pragma unroll
;             for (int w = 0; w < 8; ++w) s += part[(w * 16 + (bj * 2 + n) * 4 + j) * 64 + lane];
;             v[bj][n][j] = s; }
;       pre(fr, fq);
;       epi(NREAL + 16 * wid + fr, cb, fq, v[0][0], v[0][1], v[1][0], v[1][1]);
	v_pk_add_f32 v[4:5], v[28:29], v[30:31]
	v_pk_add_f32 v[2:3], v[2:3], v[6:7]
	s_waitcnt lgkmcnt(5)
	v_pk_add_f32 v[4:5], v[4:5], v[32:33]
	v_pk_add_f32 v[2:3], v[2:3], v[8:9]
	s_waitcnt lgkmcnt(4)
	v_pk_add_f32 v[4:5], v[4:5], v[34:35]
	v_pk_add_f32 v[2:3], v[2:3], v[10:11]
	s_waitcnt lgkmcnt(3)
	v_pk_add_f32 v[4:5], v[4:5], v[36:37]
	v_pk_add_f32 v[2:3], v[2:3], v[12:13]
	s_waitcnt lgkmcnt(2)
	v_pk_add_f32 v[4:5], v[4:5], v[38:39]
	v_pk_add_f32 v[2:3], v[2:3], v[14:15]
	s_waitcnt lgkmcnt(1)
	v_pk_add_f32 v[4:5], v[4:5], v[40:41]
	v_pk_add_f32 v[28:29], v[2:3], v[16:17]
	s_waitcnt lgkmcnt(0)
	v_pk_add_f32 v[30:31], v[4:5], v[44:45]
	ds_read2st64_b32 v[2:3], v42 offset0:8 offset1:9
	ds_read2st64_b32 v[4:5], v42 offset0:24 offset1:25
	ds_read2st64_b32 v[6:7], v42 offset0:40 offset1:41
	ds_read2st64_b32 v[8:9], v42 offset0:56 offset1:57
	ds_read2st64_b32 v[10:11], v42 offset0:72 offset1:73
	ds_read2st64_b32 v[12:13], v42 offset0:88 offset1:89
	ds_read2st64_b32 v[14:15], v42 offset0:104 offset1:105
	ds_read2st64_b32 v[16:17], v42 offset0:120 offset1:121
	ds_read2st64_b32 v[32:33], v42 offset0:10 offset1:11
	ds_read2st64_b32 v[34:35], v42 offset0:26 offset1:27
	ds_read2st64_b32 v[36:37], v42 offset0:42 offset1:43
	ds_read2st64_b32 v[38:39], v42 offset0:58 offset1:59
	ds_read2st64_b32 v[40:41], v42 offset0:74 offset1:75
	ds_read2st64_b32 v[44:45], v42 offset0:90 offset1:91
	ds_read2st64_b32 v[46:47], v42 offset0:106 offset1:107
	ds_read2st64_b32 v[48:49], v42 offset0:122 offset1:123
	s_waitcnt lgkmcnt(7)
	v_pk_add_f32 v[32:33], v[32:33], 0 op_sel_hi:[1,0]
	v_pk_add_f32 v[2:3], v[2:3], 0 op_sel_hi:[1,0]
	s_nop 0
	v_pk_add_f32 v[2:3], v[2:3], v[4:5]
	s_waitcnt lgkmcnt(6)
	v_pk_add_f32 v[4:5], v[32:33], v[34:35]
	v_pk_add_f32 v[2:3], v[2:3], v[6:7]
	s_waitcnt lgkmcnt(5)
	v_pk_add_f32 v[4:5], v[4:5], v[36:37]
	v_pk_add_f32 v[2:3], v[2:3], v[8:9]
	s_waitcnt lgkmcnt(4)
	v_pk_add_f32 v[4:5], v[4:5], v[38:39]
	v_pk_add_f32 v[2:3], v[2:3], v[10:11]
	s_waitcnt lgkmcnt(3)
	v_pk_add_f32 v[4:5], v[4:5], v[40:41]
	v_pk_add_f32 v[2:3], v[2:3], v[12:13]
	s_waitcnt lgkmcnt(2)
	v_pk_add_f32 v[4:5], v[4:5], v[44:45]
	v_pk_add_f32 v[2:3], v[2:3], v[14:15]
	s_waitcnt lgkmcnt(1)
	v_pk_add_f32 v[4:5], v[4:5], v[46:47]
	v_pk_add_f32 v[32:33], v[2:3], v[16:17]
	s_waitcnt lgkmcnt(0)
	v_pk_add_f32 v[34:35], v[4:5], v[48:49]
	ds_read2st64_b32 v[2:3], v42 offset0:12 offset1:13
	ds_read2st64_b32 v[4:5], v42 offset0:28 offset1:29
	ds_read2st64_b32 v[6:7], v42 offset0:44 offset1:45
	ds_read2st64_b32 v[8:9], v42 offset0:60 offset1:61
	ds_read2st64_b32 v[10:11], v42 offset0:76 offset1:77
	ds_read2st64_b32 v[12:13], v42 offset0:92 offset1:93
	ds_read2st64_b32 v[14:15], v42 offset0:108 offset1:109
	ds_read2st64_b32 v[16:17], v42 offset0:124 offset1:125
	ds_read2st64_b32 v[36:37], v42 offset0:14 offset1:15
	ds_read2st64_b32 v[38:39], v42 offset0:30 offset1:31
	ds_read2st64_b32 v[40:41], v42 offset0:46 offset1:47
	ds_read2st64_b32 v[44:45], v42 offset0:62 offset1:63
	ds_read2st64_b32 v[46:47], v42 offset0:78 offset1:79
	ds_read2st64_b32 v[48:49], v42 offset0:94 offset1:95
	ds_read2st64_b32 v[50:51], v42 offset0:110 offset1:111
	ds_read2st64_b32 v[52:53], v42 offset0:126 offset1:127
	s_waitcnt lgkmcnt(7)
	v_pk_add_f32 v[36:37], v[36:37], 0 op_sel_hi:[1,0]
	v_pk_add_f32 v[2:3], v[2:3], 0 op_sel_hi:[1,0]
	s_nop 0
	v_pk_add_f32 v[2:3], v[2:3], v[4:5]
	s_waitcnt lgkmcnt(6)
	v_pk_add_f32 v[4:5], v[36:37], v[38:39]
	v_pk_add_f32 v[2:3], v[2:3], v[6:7]
	s_waitcnt lgkmcnt(5)
	v_pk_add_f32 v[4:5], v[4:5], v[40:41]
	v_pk_add_f32 v[2:3], v[2:3], v[8:9]
	s_waitcnt lgkmcnt(4)
	v_pk_add_f32 v[4:5], v[4:5], v[44:45]
	v_pk_add_f32 v[2:3], v[2:3], v[10:11]
	s_waitcnt lgkmcnt(3)
	v_pk_add_f32 v[4:5], v[4:5], v[46:47]
	v_pk_add_f32 v[2:3], v[2:3], v[12:13]
	s_waitcnt lgkmcnt(2)
	v_pk_add_f32 v[4:5], v[4:5], v[48:49]
	v_pk_add_f32 v[2:3], v[2:3], v[14:15]
	s_waitcnt lgkmcnt(1)
	v_pk_add_f32 v[4:5], v[4:5], v[50:51]
	v_lshl_add_u64 v[40:41], s[4:5], 2, v[26:27]
	v_pk_add_f32 v[36:37], v[2:3], v[16:17]
	s_waitcnt lgkmcnt(0)
	v_pk_add_f32 v[38:39], v[4:5], v[52:53]
	global_load_dwordx4 v[2:5], v[40:41], off
	global_load_dwordx4 v[6:9], v[40:41], off offset:64
	global_load_dwordx4 v[10:13], v[40:41], off offset:512
	global_load_dwordx4 v[14:17], v[40:41], off offset:576
	s_waitcnt vmcnt(3)
	v_pk_add_f32 v[4:5], v[20:21], v[4:5]
	v_pk_add_f32 v[2:3], v[18:19], v[2:3]
	global_store_dwordx4 v[40:41], v[2:5], off
	s_waitcnt vmcnt(3)
	s_nop 0
	v_pk_add_f32 v[4:5], v[30:31], v[8:9]
	v_pk_add_f32 v[2:3], v[28:29], v[6:7]
	global_store_dwordx4 v[40:41], v[2:5], off offset:64
	s_waitcnt vmcnt(3)
	s_nop 0
	v_pk_add_f32 v[4:5], v[34:35], v[12:13]
	v_pk_add_f32 v[2:3], v[32:33], v[10:11]
	global_store_dwordx4 v[40:41], v[2:5], off offset:512
	s_waitcnt vmcnt(3)
	s_nop 0
	v_pk_add_f32 v[4:5], v[38:39], v[16:17]
	v_pk_add_f32 v[2:3], v[36:37], v[14:15]
	global_store_dwordx4 v[40:41], v[2:5], off offset:576
	s_branch .LBB0_1546
